# stack12 + redundant s_waitcnt lgkmcnt(0) after each pre-MFMA barrier removed from the six GEMM K-loops
# speedup vs baseline: 1.0011x; 1.0011x over previous
; #define PG8_STAGE(bufoff, gbase, voff) do { _Pragma("unroll") for (int _i = 0; _i < 2; ++_i) \
;         __builtin_amdgcn_global_load_lds((const unsigned*)((const char*)(gbase) + (voff)[_i]), (PG8_LAS unsigned*)(lds + (bufoff) + ldsw + _i * 8192), 16, 0, 0); } while (0)
; #define PG8_LDA(dst, b, h) do { _Pragma("unroll") for (int m = 0; m < 4; ++m) _Pragma("unroll") for (int k = 0; k < 2; ++k) dst[m][k] = *(const PG8_LAS bf16x8*)(lds + PG8_SA(b, h) + aoff + m * 2048 + k * 1024); } while (0)
; #define PG8_LDB(dst, b, h) do { _Pragma("unroll") for (int n = 0; n < 2; ++n) _Pragma("unroll") for (int k = 0; k < 2; ++k) dst[n][k] = *(const PG8_LAS bf16x8*)(lds + PG8_SB(b, h) + boff + n * 2048 + k * 1024); } while (0)
; #define PG8_MMA(ai, bj, At, Bt) do { __builtin_amdgcn_s_setprio(1); _Pragma("unroll") for (int m = 0; m < 4; ++m) _Pragma("unroll") for (int n = 0; n < 2; ++n) _Pragma("unroll") for (int k = 0; k < 2; ++k) \
;         acc[ai][bj][m][n] = __builtin_amdgcn_mfma_f32_16x16x32_bf16(Bt[n][k], At[m][k], acc[ai][bj][m][n], 0, 0, 0); __builtin_amdgcn_s_setprio(0); } while (0)
; #define PG8_WAIT_V(n) asm volatile("s_waitcnt vmcnt(" #n ")" ::: "memory")
; #define PG8_BAR __builtin_amdgcn_s_barrier()
; template <class Epi, class Sched, bool ALIGN_EPI = false, bool SP2 = false>
; __device__ __forceinline__ void gemm_phase(PG8_LAS unsigned char* lds, const Gemm g, const Sched& S, const Epi& E, int wid_in) {
;     ...
;         for (int t = 0; t < nt; t += 2) {
;             const bool last = (t == nt - 2);
;             const char* a1 = cA + (size_t)(t + 1) * kstep;
;             const char* a2 = last ? nA : cA + (size_t)(t + 2) * kstep; const char* b2 = last ? nB : cB + (size_t)(t + 2) * kstep;
;             const char* a3 = a2 + kstep; const char* b3 = b2 + kstep;
;             if (last && has_next) S.a_ready(nxt);
;             if constexpr (SP2) {
;             PG8_LDB(B0, 0, 0); PG8_LDB(B1, 0, 1); PG8_SCHED; PG8_LDA(At, 0, 0); PG8_STAGE(PG8_SA(1, 1), a1 + hstep, voffA);
;             PG8_WAIT_V(8); PG8_WAIT_L(0); PG8_BAR; PG8_MMA(0, 0, At, B0); PG8_MMA(0, 1, At, B1); PG8_BAR; PG8_SCHED;
;             PG8_LDA(At, 0, 1); PG8_STAGE(PG8_SB(0, 0), b2, voffB); PG8_STAGE(PG8_SB(0, 1), b2 + hstep, voffB); PG8_STAGE(PG8_SA(0, 0), a2, voffA);
;             PG8_WAIT_V(8); PG8_WAIT_L(0); PG8_BAR; PG8_MMA(1, 0, At, B0); PG8_MMA(1, 1, At, B1); PG8_BAR; PG8_SCHED;
.Lprio_skip_0:
.LBB0_278:
	s_add_u32 s28, s26, 0xfff80080
	s_addc_u32 s29, s27, -1
	s_add_i32 s40, 0, 0x10000
	s_cmp_eq_u32 s63, 28
	s_cselect_b32 s31, s11, s29
	s_cselect_b32 s30, s19, s28
	s_cselect_b32 s29, s17, s65
	s_cselect_b32 s28, s62, s64
	s_add_i32 s41, 0, 0x14000
	v_add_u32_e32 v154, s40, v140
	v_add_u32_e32 v170, s41, v140
	ds_read_b128 v[142:145], v154
	ds_read_b128 v[146:149], v154 offset:1024
	ds_read_b128 v[150:153], v154 offset:2048
	ds_read_b128 v[154:157], v154 offset:3072
	ds_read_b128 v[158:161], v170
	ds_read_b128 v[162:165], v170 offset:1024
	ds_read_b128 v[166:169], v170 offset:2048
	ds_read_b128 v[170:173], v170 offset:3072
	v_lshl_add_u64 v[220:221], s[26:27], 0, v[138:139]
	s_add_i32 m0, s13, 0xc000
	ds_read_b128 v[174:177], v141
	ds_read_b128 v[178:181], v141 offset:1024
	ds_read_b128 v[182:185], v141 offset:2048
	ds_read_b128 v[186:189], v141 offset:3072
	ds_read_b128 v[190:193], v141 offset:4096
	ds_read_b128 v[208:211], v141 offset:5120
	ds_read_b128 v[212:215], v141 offset:6144
	ds_read_b128 v[216:219], v141 offset:7168
	global_load_lds_dwordx4 v[220:221], off
	v_lshl_add_u64 v[220:221], s[26:27], 0, v[136:137]
	s_add_i32 m0, s13, 0xe000
	s_nop 0
	global_load_lds_dwordx4 v[220:221], off
	s_waitcnt vmcnt(8)
	s_waitcnt lgkmcnt(0)
	s_barrier
	v_mfma_f32_16x16x32_bf16 v[126:129], v[142:145], v[174:177], v[126:129]
	v_mfma_f32_16x16x32_bf16 v[122:125], v[150:153], v[174:177], v[122:125]
	v_mfma_f32_16x16x32_bf16 v[118:121], v[142:145], v[182:185], v[118:121]
	v_mfma_f32_16x16x32_bf16 v[114:117], v[150:153], v[182:185], v[114:117]
	v_mfma_f32_16x16x32_bf16 v[102:105], v[142:145], v[190:193], v[102:105]
	v_mfma_f32_16x16x32_bf16 v[98:101], v[150:153], v[190:193], v[98:101]
	v_mfma_f32_16x16x32_bf16 v[86:89], v[142:145], v[212:215], v[86:89]
	v_mfma_f32_16x16x32_bf16 v[82:85], v[150:153], v[212:215], v[82:85]
	v_mfma_f32_16x16x32_bf16 v[126:129], v[146:149], v[178:181], v[126:129]
	v_mfma_f32_16x16x32_bf16 v[122:125], v[154:157], v[178:181], v[122:125]
	v_mfma_f32_16x16x32_bf16 v[118:121], v[146:149], v[186:189], v[118:121]
	v_mfma_f32_16x16x32_bf16 v[114:117], v[154:157], v[186:189], v[114:117]
	v_mfma_f32_16x16x32_bf16 v[102:105], v[146:149], v[208:211], v[102:105]
	v_mfma_f32_16x16x32_bf16 v[98:101], v[154:157], v[208:211], v[98:101]
	v_mfma_f32_16x16x32_bf16 v[86:89], v[146:149], v[216:219], v[86:89]
	v_mfma_f32_16x16x32_bf16 v[82:85], v[154:157], v[216:219], v[82:85]
	v_mfma_f32_16x16x32_bf16 v[110:113], v[158:161], v[174:177], v[110:113]
	v_mfma_f32_16x16x32_bf16 v[106:109], v[166:169], v[174:177], v[106:109]
	v_mfma_f32_16x16x32_bf16 v[94:97], v[158:161], v[182:185], v[94:97]
	v_mfma_f32_16x16x32_bf16 v[90:93], v[166:169], v[182:185], v[90:93]
	v_mfma_f32_16x16x32_bf16 v[78:81], v[158:161], v[190:193], v[78:81]
	v_mfma_f32_16x16x32_bf16 v[74:77], v[166:169], v[190:193], v[74:77]
	v_mfma_f32_16x16x32_bf16 v[70:73], v[158:161], v[212:215], v[70:73]
	v_mfma_f32_16x16x32_bf16 v[66:69], v[166:169], v[212:215], v[66:69]
	v_mfma_f32_16x16x32_bf16 v[110:113], v[162:165], v[178:181], v[110:113]
	v_mfma_f32_16x16x32_bf16 v[106:109], v[170:173], v[178:181], v[106:109]
	v_mfma_f32_16x16x32_bf16 v[94:97], v[162:165], v[186:189], v[94:97]
	v_mfma_f32_16x16x32_bf16 v[90:93], v[170:173], v[186:189], v[90:93]
	v_mfma_f32_16x16x32_bf16 v[78:81], v[162:165], v[208:211], v[78:81]
	v_mfma_f32_16x16x32_bf16 v[74:77], v[170:173], v[208:211], v[74:77]
	v_mfma_f32_16x16x32_bf16 v[70:73], v[162:165], v[216:219], v[70:73]
	v_mfma_f32_16x16x32_bf16 v[66:69], v[170:173], v[216:219], v[66:69]
	s_barrier
	s_add_i32 s40, s40, s59
	v_lshl_add_u64 v[220:221], s[28:29], 0, v[0:1]
	s_mov_b32 m0, s40
	ds_read_b128 v[174:177], v141 offset:16384
	ds_read_b128 v[178:181], v141 offset:17408
	ds_read_b128 v[182:185], v141 offset:18432
	ds_read_b128 v[186:189], v141 offset:19456
	ds_read_b128 v[190:193], v141 offset:20480
	ds_read_b128 v[208:211], v141 offset:21504
	ds_read_b128 v[212:215], v141 offset:22528
	ds_read_b128 v[216:219], v141 offset:23552
	global_load_lds_dwordx4 v[220:221], off
	s_add_i32 m0, s40, 0x2000
	s_add_u32 s72, s28, 0x80000
	v_lshl_add_u64 v[222:223], s[28:29], 0, v[134:135]
	s_addc_u32 s73, s29, 0
	s_add_i32 s40, s41, s59
	global_load_lds_dwordx4 v[222:223], off
	v_lshl_add_u64 v[224:225], s[72:73], 0, v[0:1]
	s_mov_b32 m0, s40
	v_lshl_add_u64 v[226:227], s[30:31], 0, v[132:133]
	global_load_lds_dwordx4 v[224:225], off
	v_lshl_add_u64 v[224:225], s[72:73], 0, v[134:135]
	s_add_i32 m0, s40, 0x2000
	s_nop 0
	global_load_lds_dwordx4 v[224:225], off
	v_lshl_add_u64 v[224:225], s[30:31], 0, v[130:131]
	s_mov_b32 m0, s13
	s_nop 0
	global_load_lds_dwordx4 v[224:225], off
	s_mov_b32 m0, s36
	s_nop 0
	global_load_lds_dwordx4 v[226:227], off
	s_waitcnt vmcnt(8)
	s_waitcnt lgkmcnt(0)
	s_barrier
; #define PG8_STAGE(bufoff, gbase, voff) do { _Pragma("unroll") for (int _i = 0; _i < 2; ++_i) \
;         __builtin_amdgcn_global_load_lds((const unsigned*)((const char*)(gbase) + (voff)[_i]), (PG8_LAS unsigned*)(lds + (bufoff) + ldsw + _i * 8192), 16, 0, 0); } while (0)
; #define PG8_LDA(dst, b, h) do { _Pragma("unroll") for (int m = 0; m < 4; ++m) _Pragma("unroll") for (int k = 0; k < 2; ++k) dst[m][k] = *(const PG8_LAS bf16x8*)(lds + PG8_SA(b, h) + aoff + m * 2048 + k * 1024); } while (0)
; #define PG8_LDB(dst, b, h) do { _Pragma("unroll") for (int n = 0; n < 2; ++n) _Pragma("unroll") for (int k = 0; k < 2; ++k) dst[n][k] = *(const PG8_LAS bf16x8*)(lds + PG8_SB(b, h) + boff + n * 2048 + k * 1024); } while (0)
; #define PG8_MMA(ai, bj, At, Bt) do { __builtin_amdgcn_s_setprio(1); _Pragma("unroll") for (int m = 0; m < 4; ++m) _Pragma("unroll") for (int n = 0; n < 2; ++n) _Pragma("unroll") for (int k = 0; k < 2; ++k) \
;         acc[ai][bj][m][n] = __builtin_amdgcn_mfma_f32_16x16x32_bf16(Bt[n][k], At[m][k], acc[ai][bj][m][n], 0, 0, 0); __builtin_amdgcn_s_setprio(0); } while (0)
; #define PG8_WAIT_V(n) asm volatile("s_waitcnt vmcnt(" #n ")" ::: "memory")
; #define PG8_WAIT_L(n) asm volatile("s_waitcnt lgkmcnt(" #n ")" ::: "memory")
; #define PG8_BAR __builtin_amdgcn_s_barrier()
; #define PG8_SCHED __builtin_amdgcn_sched_barrier(0)
; template <class Epi, class Sched, bool ALIGN_EPI = false, bool SP2 = false>
; __device__ __forceinline__ void gemm_phase(PG8_LAS unsigned char* lds, const Gemm g, const Sched& S, const Epi& E, int wid_in) {
;     ...
;             PG8_WAIT_V(8); PG8_WAIT_L(0); PG8_BAR; PG8_MMA(1, 0, At, B0); PG8_MMA(1, 1, At, B1); PG8_BAR; PG8_SCHED;
;             PG8_LDB(B0, 1, 0); PG8_LDB(B1, 1, 1); PG8_SCHED; PG8_LDA(At, 1, 0); PG8_STAGE(PG8_SA(0, 1), a2 + hstep, voffA);
;             PG8_WAIT_V(8); PG8_WAIT_L(0); PG8_BAR; PG8_MMA(0, 0, At, B0); PG8_MMA(0, 1, At, B1); PG8_BAR; PG8_SCHED;
	v_mfma_f32_16x16x32_bf16 v[62:65], v[142:145], v[174:177], v[62:65]
	v_mfma_f32_16x16x32_bf16 v[58:61], v[150:153], v[174:177], v[58:61]
	v_mfma_f32_16x16x32_bf16 v[54:57], v[142:145], v[182:185], v[54:57]
	v_mfma_f32_16x16x32_bf16 v[50:53], v[150:153], v[182:185], v[50:53]
	v_mfma_f32_16x16x32_bf16 v[38:41], v[142:145], v[190:193], v[38:41]
	v_mfma_f32_16x16x32_bf16 v[34:37], v[150:153], v[190:193], v[34:37]
	v_mfma_f32_16x16x32_bf16 v[22:25], v[142:145], v[212:215], v[22:25]
	v_mfma_f32_16x16x32_bf16 v[18:21], v[150:153], v[212:215], v[18:21]
	v_mfma_f32_16x16x32_bf16 v[62:65], v[146:149], v[178:181], v[62:65]
	v_mfma_f32_16x16x32_bf16 v[58:61], v[154:157], v[178:181], v[58:61]
	v_mfma_f32_16x16x32_bf16 v[54:57], v[146:149], v[186:189], v[54:57]
	v_mfma_f32_16x16x32_bf16 v[50:53], v[154:157], v[186:189], v[50:53]
	v_mfma_f32_16x16x32_bf16 v[38:41], v[146:149], v[208:211], v[38:41]
	v_mfma_f32_16x16x32_bf16 v[34:37], v[154:157], v[208:211], v[34:37]
	v_mfma_f32_16x16x32_bf16 v[22:25], v[146:149], v[216:219], v[22:25]
	v_mfma_f32_16x16x32_bf16 v[18:21], v[154:157], v[216:219], v[18:21]
	v_mfma_f32_16x16x32_bf16 v[46:49], v[158:161], v[174:177], v[46:49]
	v_mfma_f32_16x16x32_bf16 v[42:45], v[166:169], v[174:177], v[42:45]
	v_mfma_f32_16x16x32_bf16 v[30:33], v[158:161], v[182:185], v[30:33]
	v_mfma_f32_16x16x32_bf16 v[26:29], v[166:169], v[182:185], v[26:29]
	v_mfma_f32_16x16x32_bf16 v[14:17], v[158:161], v[190:193], v[14:17]
	v_mfma_f32_16x16x32_bf16 v[10:13], v[166:169], v[190:193], v[10:13]
	v_mfma_f32_16x16x32_bf16 v[6:9], v[158:161], v[212:215], v[6:9]
	v_mfma_f32_16x16x32_bf16 v[2:5], v[166:169], v[212:215], v[2:5]
	v_mfma_f32_16x16x32_bf16 v[46:49], v[162:165], v[178:181], v[46:49]
	v_mfma_f32_16x16x32_bf16 v[42:45], v[170:173], v[178:181], v[42:45]
	v_mfma_f32_16x16x32_bf16 v[30:33], v[162:165], v[186:189], v[30:33]
	v_mfma_f32_16x16x32_bf16 v[26:29], v[170:173], v[186:189], v[26:29]
	v_mfma_f32_16x16x32_bf16 v[14:17], v[162:165], v[208:211], v[14:17]
	v_mfma_f32_16x16x32_bf16 v[10:13], v[170:173], v[208:211], v[10:13]
	v_mfma_f32_16x16x32_bf16 v[6:9], v[162:165], v[216:219], v[6:9]
	v_mfma_f32_16x16x32_bf16 v[2:5], v[170:173], v[216:219], v[2:5]
	s_barrier
	s_add_i32 s40, 0, 0x18000
	s_add_i32 s41, 0, 0x1c000
	v_add_u32_e32 v154, s40, v140
	v_add_u32_e32 v170, s41, v140
	ds_read_b128 v[142:145], v154
	ds_read_b128 v[146:149], v154 offset:1024
	ds_read_b128 v[150:153], v154 offset:2048
	ds_read_b128 v[154:157], v154 offset:3072
	ds_read_b128 v[158:161], v170
	ds_read_b128 v[162:165], v170 offset:1024
	ds_read_b128 v[166:169], v170 offset:2048
	ds_read_b128 v[170:173], v170 offset:3072
	s_add_u32 s30, s30, 0x80000
	s_addc_u32 s31, s31, 0
	s_mov_b32 m0, s37
	v_lshl_add_u64 v[228:229], s[30:31], 0, v[130:131]
	ds_read_b128 v[174:177], v141 offset:32768
	ds_read_b128 v[178:181], v141 offset:33792
	ds_read_b128 v[182:185], v141 offset:34816
	ds_read_b128 v[186:189], v141 offset:35840
	ds_read_b128 v[190:193], v141 offset:36864
	ds_read_b128 v[208:211], v141 offset:37888
	ds_read_b128 v[212:215], v141 offset:38912
	ds_read_b128 v[216:219], v141 offset:39936
	global_load_lds_dwordx4 v[228:229], off
	v_lshl_add_u64 v[228:229], s[30:31], 0, v[132:133]
	s_mov_b32 m0, s38
	s_nop 0
	global_load_lds_dwordx4 v[228:229], off
	s_waitcnt vmcnt(8)
	s_waitcnt lgkmcnt(0)
	s_barrier
	v_mfma_f32_16x16x32_bf16 v[126:129], v[142:145], v[174:177], v[126:129]
	v_mfma_f32_16x16x32_bf16 v[122:125], v[150:153], v[174:177], v[122:125]
	v_mfma_f32_16x16x32_bf16 v[118:121], v[142:145], v[182:185], v[118:121]
	v_mfma_f32_16x16x32_bf16 v[114:117], v[150:153], v[182:185], v[114:117]
	v_mfma_f32_16x16x32_bf16 v[102:105], v[142:145], v[190:193], v[102:105]
	v_mfma_f32_16x16x32_bf16 v[98:101], v[150:153], v[190:193], v[98:101]
	v_mfma_f32_16x16x32_bf16 v[86:89], v[142:145], v[212:215], v[86:89]
	v_mfma_f32_16x16x32_bf16 v[82:85], v[150:153], v[212:215], v[82:85]
	v_mfma_f32_16x16x32_bf16 v[126:129], v[146:149], v[178:181], v[126:129]
	v_mfma_f32_16x16x32_bf16 v[122:125], v[154:157], v[178:181], v[122:125]
	v_mfma_f32_16x16x32_bf16 v[118:121], v[146:149], v[186:189], v[118:121]
	v_mfma_f32_16x16x32_bf16 v[114:117], v[154:157], v[186:189], v[114:117]
	v_mfma_f32_16x16x32_bf16 v[102:105], v[146:149], v[208:211], v[102:105]
	v_mfma_f32_16x16x32_bf16 v[98:101], v[154:157], v[208:211], v[98:101]
	v_mfma_f32_16x16x32_bf16 v[86:89], v[146:149], v[216:219], v[86:89]
	v_mfma_f32_16x16x32_bf16 v[82:85], v[154:157], v[216:219], v[82:85]
	v_mfma_f32_16x16x32_bf16 v[110:113], v[158:161], v[174:177], v[110:113]
	v_mfma_f32_16x16x32_bf16 v[106:109], v[166:169], v[174:177], v[106:109]
	v_mfma_f32_16x16x32_bf16 v[94:97], v[158:161], v[182:185], v[94:97]
	v_mfma_f32_16x16x32_bf16 v[90:93], v[166:169], v[182:185], v[90:93]
	v_mfma_f32_16x16x32_bf16 v[78:81], v[158:161], v[190:193], v[78:81]
	v_mfma_f32_16x16x32_bf16 v[74:77], v[166:169], v[190:193], v[74:77]
	v_mfma_f32_16x16x32_bf16 v[70:73], v[158:161], v[212:215], v[70:73]
	v_mfma_f32_16x16x32_bf16 v[66:69], v[166:169], v[212:215], v[66:69]
	v_mfma_f32_16x16x32_bf16 v[110:113], v[162:165], v[178:181], v[110:113]
	v_mfma_f32_16x16x32_bf16 v[106:109], v[170:173], v[178:181], v[106:109]
	v_mfma_f32_16x16x32_bf16 v[94:97], v[162:165], v[186:189], v[94:97]
	v_mfma_f32_16x16x32_bf16 v[90:93], v[170:173], v[186:189], v[90:93]
	v_mfma_f32_16x16x32_bf16 v[78:81], v[162:165], v[208:211], v[78:81]
	v_mfma_f32_16x16x32_bf16 v[74:77], v[170:173], v[208:211], v[74:77]
	v_mfma_f32_16x16x32_bf16 v[70:73], v[162:165], v[216:219], v[70:73]
	v_mfma_f32_16x16x32_bf16 v[66:69], v[170:173], v[216:219], v[66:69]
	s_barrier
; #define PG8_STAGE(bufoff, gbase, voff) do { _Pragma("unroll") for (int _i = 0; _i < 2; ++_i) \
;         __builtin_amdgcn_global_load_lds((const unsigned*)((const char*)(gbase) + (voff)[_i]), (PG8_LAS unsigned*)(lds + (bufoff) + ldsw + _i * 8192), 16, 0, 0); } while (0)
; #define PG8_LDA(dst, b, h) do { _Pragma("unroll") for (int m = 0; m < 4; ++m) _Pragma("unroll") for (int k = 0; k < 2; ++k) dst[m][k] = *(const PG8_LAS bf16x8*)(lds + PG8_SA(b, h) + aoff + m * 2048 + k * 1024); } while (0)
; #define PG8_MMA(ai, bj, At, Bt) do { __builtin_amdgcn_s_setprio(1); _Pragma("unroll") for (int m = 0; m < 4; ++m) _Pragma("unroll") for (int n = 0; n < 2; ++n) _Pragma("unroll") for (int k = 0; k < 2; ++k) \
;         acc[ai][bj][m][n] = __builtin_amdgcn_mfma_f32_16x16x32_bf16(Bt[n][k], At[m][k], acc[ai][bj][m][n], 0, 0, 0); __builtin_amdgcn_s_setprio(0); } while (0)
; #define PG8_WAIT_V(n) asm volatile("s_waitcnt vmcnt(" #n ")" ::: "memory")
; #define PG8_WAIT_L(n) asm volatile("s_waitcnt lgkmcnt(" #n ")" ::: "memory")
; #define PG8_BAR __builtin_amdgcn_s_barrier()
; #define PG8_SCHED __builtin_amdgcn_sched_barrier(0)
; template <class Epi, class Sched, bool ALIGN_EPI = false, bool SP2 = false>
; __device__ __forceinline__ void gemm_phase(PG8_LAS unsigned char* lds, const Gemm g, const Sched& S, const Epi& E, int wid_in) {
;     ...
;             PG8_LDA(At, 1, 1); PG8_STAGE(PG8_SB(1, 0), b3, voffB); PG8_STAGE(PG8_SB(1, 1), b3 + hstep, voffB); PG8_STAGE(PG8_SA(1, 0), a3, voffA);
;             PG8_WAIT_V(8); PG8_WAIT_L(0); PG8_BAR; PG8_MMA(1, 0, At, B0); PG8_MMA(1, 1, At, B1); PG8_BAR; PG8_SCHED;
	s_add_i32 s30, s40, s59
	v_lshl_add_u64 v[220:221], v[220:221], 0, s[94:95]
	s_mov_b32 m0, s30
	ds_read_b128 v[174:177], v141 offset:49152
	ds_read_b128 v[178:181], v141 offset:50176
	ds_read_b128 v[182:185], v141 offset:51200
	ds_read_b128 v[186:189], v141 offset:52224
	ds_read_b128 v[190:193], v141 offset:53248
	ds_read_b128 v[208:211], v141 offset:54272
	ds_read_b128 v[212:215], v141 offset:55296
	ds_read_b128 v[216:219], v141 offset:56320
	global_load_lds_dwordx4 v[220:221], off
	s_add_i32 m0, s30, 0x2000
	s_add_u32 s28, s28, 0x80080
	v_lshl_add_u64 v[220:221], v[222:223], 0, s[94:95]
	s_addc_u32 s29, s29, 0
	s_add_i32 s30, s41, s59
	global_load_lds_dwordx4 v[220:221], off
	v_lshl_add_u64 v[220:221], s[28:29], 0, v[0:1]
	s_mov_b32 m0, s30
	s_nop 0
	global_load_lds_dwordx4 v[220:221], off
	v_lshl_add_u64 v[220:221], s[28:29], 0, v[134:135]
	s_add_i32 m0, s30, 0x2000
	s_nop 0
	global_load_lds_dwordx4 v[220:221], off
	v_lshl_add_u64 v[220:221], v[224:225], 0, s[94:95]
	s_mov_b32 m0, s52
	s_nop 0
	global_load_lds_dwordx4 v[220:221], off
	v_lshl_add_u64 v[220:221], v[226:227], 0, s[94:95]
	s_mov_b32 m0, s53
	s_nop 0
	global_load_lds_dwordx4 v[220:221], off
	s_waitcnt vmcnt(8)
	s_waitcnt lgkmcnt(0)
	s_barrier
	v_mfma_f32_16x16x32_bf16 v[62:65], v[142:145], v[174:177], v[62:65]
	v_mfma_f32_16x16x32_bf16 v[58:61], v[150:153], v[174:177], v[58:61]
	v_mfma_f32_16x16x32_bf16 v[54:57], v[142:145], v[182:185], v[54:57]
	v_mfma_f32_16x16x32_bf16 v[50:53], v[150:153], v[182:185], v[50:53]
	v_mfma_f32_16x16x32_bf16 v[38:41], v[142:145], v[190:193], v[38:41]
	v_mfma_f32_16x16x32_bf16 v[34:37], v[150:153], v[190:193], v[34:37]
	v_mfma_f32_16x16x32_bf16 v[22:25], v[142:145], v[212:215], v[22:25]
	v_mfma_f32_16x16x32_bf16 v[18:21], v[150:153], v[212:215], v[18:21]
	v_mfma_f32_16x16x32_bf16 v[62:65], v[146:149], v[178:181], v[62:65]
	v_mfma_f32_16x16x32_bf16 v[58:61], v[154:157], v[178:181], v[58:61]
	v_mfma_f32_16x16x32_bf16 v[54:57], v[146:149], v[186:189], v[54:57]
	v_mfma_f32_16x16x32_bf16 v[50:53], v[154:157], v[186:189], v[50:53]
	v_mfma_f32_16x16x32_bf16 v[38:41], v[146:149], v[208:211], v[38:41]
	v_mfma_f32_16x16x32_bf16 v[34:37], v[154:157], v[208:211], v[34:37]
	v_mfma_f32_16x16x32_bf16 v[22:25], v[146:149], v[216:219], v[22:25]
	v_mfma_f32_16x16x32_bf16 v[18:21], v[154:157], v[216:219], v[18:21]
	v_mfma_f32_16x16x32_bf16 v[46:49], v[158:161], v[174:177], v[46:49]
	v_mfma_f32_16x16x32_bf16 v[42:45], v[166:169], v[174:177], v[42:45]
	v_mfma_f32_16x16x32_bf16 v[30:33], v[158:161], v[182:185], v[30:33]
	v_mfma_f32_16x16x32_bf16 v[26:29], v[166:169], v[182:185], v[26:29]
	v_mfma_f32_16x16x32_bf16 v[14:17], v[158:161], v[190:193], v[14:17]
	v_mfma_f32_16x16x32_bf16 v[10:13], v[166:169], v[190:193], v[10:13]
	v_mfma_f32_16x16x32_bf16 v[6:9], v[158:161], v[212:215], v[6:9]
	v_mfma_f32_16x16x32_bf16 v[2:5], v[166:169], v[212:215], v[2:5]
	v_mfma_f32_16x16x32_bf16 v[46:49], v[162:165], v[178:181], v[46:49]
	v_mfma_f32_16x16x32_bf16 v[42:45], v[170:173], v[178:181], v[42:45]
	v_mfma_f32_16x16x32_bf16 v[30:33], v[162:165], v[186:189], v[30:33]
	v_mfma_f32_16x16x32_bf16 v[26:29], v[170:173], v[186:189], v[26:29]
	v_mfma_f32_16x16x32_bf16 v[14:17], v[162:165], v[208:211], v[14:17]
	v_mfma_f32_16x16x32_bf16 v[10:13], v[170:173], v[208:211], v[10:13]
	v_mfma_f32_16x16x32_bf16 v[6:9], v[162:165], v[216:219], v[6:9]
	v_mfma_f32_16x16x32_bf16 v[2:5], v[170:173], v[216:219], v[2:5]
	s_barrier
	s_add_i32 s63, s63, 2
	s_add_u32 s64, s64, 0x100
	s_addc_u32 s65, s65, 0
	s_add_u32 s26, s26, 0x100
	s_addc_u32 s27, s27, 0
	s_cmp_gt_u32 s63, 29
	s_cbranch_scc0 .LBB0_278
	s_setprio 0
	s_and_b64 vcc, exec, s[14:15]
	s_cbranch_vccz .LBB0_281
	s_barrier

; #define PG8_STAGE(bufoff, gbase, voff) do { _Pragma("unroll") for (int _i = 0; _i < 2; ++_i) \
;         __builtin_amdgcn_global_load_lds((const unsigned*)((const char*)(gbase) + (voff)[_i]), (PG8_LAS unsigned*)(lds + (bufoff) + ldsw + _i * 8192), 16, 0, 0); } while (0)
; #define PG8_LDA(dst, b, h) do { _Pragma("unroll") for (int m = 0; m < 4; ++m) _Pragma("unroll") for (int k = 0; k < 2; ++k) dst[m][k] = *(const PG8_LAS bf16x8*)(lds + PG8_SA(b, h) + aoff + m * 2048 + k * 1024); } while (0)
; #define PG8_LDB(dst, b, h) do { _Pragma("unroll") for (int n = 0; n < 2; ++n) _Pragma("unroll") for (int k = 0; k < 2; ++k) dst[n][k] = *(const PG8_LAS bf16x8*)(lds + PG8_SB(b, h) + boff + n * 2048 + k * 1024); } while (0)
; #define PG8_MMA(ai, bj, At, Bt) do { __builtin_amdgcn_s_setprio(1); _Pragma("unroll") for (int m = 0; m < 4; ++m) _Pragma("unroll") for (int n = 0; n < 2; ++n) _Pragma("unroll") for (int k = 0; k < 2; ++k) \
;         acc[ai][bj][m][n] = __builtin_amdgcn_mfma_f32_16x16x32_bf16(Bt[n][k], At[m][k], acc[ai][bj][m][n], 0, 0, 0); __builtin_amdgcn_s_setprio(0); } while (0)
; #define PG8_WAIT_V(n) asm volatile("s_waitcnt vmcnt(" #n ")" ::: "memory")
; #define PG8_BAR __builtin_amdgcn_s_barrier()
; template <class Epi, class Sched, bool ALIGN_EPI = false, bool SP2 = false>
; __device__ __forceinline__ void gemm_phase(PG8_LAS unsigned char* lds, const Gemm g, const Sched& S, const Epi& E, int wid_in) {
;     ...
;         for (int t = 0; t < nt; t += 2) {
;             const bool last = (t == nt - 2);
;             const char* a1 = cA + (size_t)(t + 1) * kstep;
;             const char* a2 = last ? nA : cA + (size_t)(t + 2) * kstep; const char* b2 = last ? nB : cB + (size_t)(t + 2) * kstep;
;             const char* a3 = a2 + kstep; const char* b3 = b2 + kstep;
;             if (last && has_next) S.a_ready(nxt);
;             if constexpr (SP2) {
;             PG8_LDB(B0, 0, 0); PG8_LDB(B1, 0, 1); PG8_SCHED; PG8_LDA(At, 0, 0); PG8_STAGE(PG8_SA(1, 1), a1 + hstep, voffA);
;             PG8_WAIT_V(8); PG8_WAIT_L(0); PG8_BAR; PG8_MMA(0, 0, At, B0); PG8_MMA(0, 1, At, B1); PG8_BAR; PG8_SCHED;
;             PG8_LDA(At, 0, 1); PG8_STAGE(PG8_SB(0, 0), b2, voffB); PG8_STAGE(PG8_SB(0, 1), b2 + hstep, voffB); PG8_STAGE(PG8_SA(0, 0), a2, voffA);
;             PG8_WAIT_V(8); PG8_WAIT_L(0); PG8_BAR; PG8_MMA(1, 0, At, B0); PG8_MMA(1, 1, At, B1); PG8_BAR; PG8_SCHED;
.Lprio_skip_1:
.LBB0_848:
	s_add_i32 s56, s34, 2
	s_add_u32 s35, s30, 0xfffc0080
	s_addc_u32 s36, s31, -1
	s_add_i32 s40, 0, 0x10000
	s_cmp_eq_u32 vcc_lo, s34
	s_cselect_b32 s37, s15, s36
	s_cselect_b32 s36, s19, s35
	s_cselect_b32 s35, s17, s63
	s_cselect_b32 s34, s27, vcc_hi
	s_add_i32 s42, 0, 0x14000
	v_add_u32_e32 v142, s40, v188
	v_add_u32_e32 v158, s42, v188
	ds_read_b128 v[130:133], v142
	ds_read_b128 v[134:137], v142 offset:1024
	ds_read_b128 v[138:141], v142 offset:2048
	ds_read_b128 v[142:145], v142 offset:3072
	ds_read_b128 v[146:149], v158
	ds_read_b128 v[150:153], v158 offset:1024
	ds_read_b128 v[154:157], v158 offset:2048
	ds_read_b128 v[158:161], v158 offset:3072
	v_lshl_add_u64 v[220:221], s[30:31], 0, v[170:171]
	s_add_i32 m0, s29, 0xc000
	ds_read_b128 v[172:175], v189
	ds_read_b128 v[176:179], v189 offset:1024
	ds_read_b128 v[180:183], v189 offset:2048
	ds_read_b128 v[184:187], v189 offset:3072
	ds_read_b128 v[190:193], v189 offset:4096
	ds_read_b128 v[208:211], v189 offset:5120
	ds_read_b128 v[212:215], v189 offset:6144
	ds_read_b128 v[216:219], v189 offset:7168
	global_load_lds_dwordx4 v[220:221], off
	v_lshl_add_u64 v[220:221], s[30:31], 0, v[168:169]
	s_add_i32 m0, s29, 0xe000
	s_nop 0
	global_load_lds_dwordx4 v[220:221], off
	s_waitcnt vmcnt(8)
	s_waitcnt lgkmcnt(0)
	s_barrier
	v_mfma_f32_16x16x32_bf16 v[126:129], v[130:133], v[172:175], v[126:129]
	v_mfma_f32_16x16x32_bf16 v[122:125], v[138:141], v[172:175], v[122:125]
	v_mfma_f32_16x16x32_bf16 v[118:121], v[130:133], v[180:183], v[118:121]
	v_mfma_f32_16x16x32_bf16 v[114:117], v[138:141], v[180:183], v[114:117]
	v_mfma_f32_16x16x32_bf16 v[102:105], v[130:133], v[190:193], v[102:105]
	v_mfma_f32_16x16x32_bf16 v[98:101], v[138:141], v[190:193], v[98:101]
	v_mfma_f32_16x16x32_bf16 v[86:89], v[130:133], v[212:215], v[86:89]
	v_mfma_f32_16x16x32_bf16 v[82:85], v[138:141], v[212:215], v[82:85]
	v_mfma_f32_16x16x32_bf16 v[126:129], v[134:137], v[176:179], v[126:129]
	v_mfma_f32_16x16x32_bf16 v[122:125], v[142:145], v[176:179], v[122:125]
	v_mfma_f32_16x16x32_bf16 v[118:121], v[134:137], v[184:187], v[118:121]
	v_mfma_f32_16x16x32_bf16 v[114:117], v[142:145], v[184:187], v[114:117]
	v_mfma_f32_16x16x32_bf16 v[102:105], v[134:137], v[208:211], v[102:105]
	v_mfma_f32_16x16x32_bf16 v[98:101], v[142:145], v[208:211], v[98:101]
	v_mfma_f32_16x16x32_bf16 v[86:89], v[134:137], v[216:219], v[86:89]
	v_mfma_f32_16x16x32_bf16 v[82:85], v[142:145], v[216:219], v[82:85]
	v_mfma_f32_16x16x32_bf16 v[110:113], v[146:149], v[172:175], v[110:113]
	v_mfma_f32_16x16x32_bf16 v[106:109], v[154:157], v[172:175], v[106:109]
	v_mfma_f32_16x16x32_bf16 v[94:97], v[146:149], v[180:183], v[94:97]
	v_mfma_f32_16x16x32_bf16 v[90:93], v[154:157], v[180:183], v[90:93]
	v_mfma_f32_16x16x32_bf16 v[78:81], v[146:149], v[190:193], v[78:81]
	v_mfma_f32_16x16x32_bf16 v[74:77], v[154:157], v[190:193], v[74:77]
	v_mfma_f32_16x16x32_bf16 v[70:73], v[146:149], v[212:215], v[70:73]
	v_mfma_f32_16x16x32_bf16 v[66:69], v[154:157], v[212:215], v[66:69]
	v_mfma_f32_16x16x32_bf16 v[110:113], v[150:153], v[176:179], v[110:113]
	v_mfma_f32_16x16x32_bf16 v[106:109], v[158:161], v[176:179], v[106:109]
	v_mfma_f32_16x16x32_bf16 v[94:97], v[150:153], v[184:187], v[94:97]
	v_mfma_f32_16x16x32_bf16 v[90:93], v[158:161], v[184:187], v[90:93]
	v_mfma_f32_16x16x32_bf16 v[78:81], v[150:153], v[208:211], v[78:81]
	v_mfma_f32_16x16x32_bf16 v[74:77], v[158:161], v[208:211], v[74:77]
	v_mfma_f32_16x16x32_bf16 v[70:73], v[150:153], v[216:219], v[70:73]
	v_mfma_f32_16x16x32_bf16 v[66:69], v[158:161], v[216:219], v[66:69]
	s_barrier
	s_add_i32 s40, s40, s59
	v_lshl_add_u64 v[220:221], s[34:35], 0, v[0:1]
	s_mov_b32 m0, s40
	ds_read_b128 v[172:175], v189 offset:16384
	ds_read_b128 v[176:179], v189 offset:17408
	ds_read_b128 v[180:183], v189 offset:18432
	ds_read_b128 v[184:187], v189 offset:19456
	ds_read_b128 v[190:193], v189 offset:20480
	ds_read_b128 v[208:211], v189 offset:21504
	ds_read_b128 v[212:215], v189 offset:22528
	ds_read_b128 v[216:219], v189 offset:23552
	global_load_lds_dwordx4 v[220:221], off
	s_add_i32 m0, s40, 0x2000
	s_add_u32 s40, s34, 0x40000
	v_lshl_add_u64 v[222:223], s[34:35], 0, v[166:167]
	s_addc_u32 s41, s35, 0
	s_add_i32 s42, s42, s59
	global_load_lds_dwordx4 v[222:223], off
	v_lshl_add_u64 v[224:225], s[40:41], 0, v[0:1]
	s_mov_b32 m0, s42
	v_lshl_add_u64 v[226:227], s[36:37], 0, v[164:165]
	global_load_lds_dwordx4 v[224:225], off
	v_lshl_add_u64 v[224:225], s[40:41], 0, v[166:167]
	s_add_i32 m0, s42, 0x2000
	s_nop 0
	global_load_lds_dwordx4 v[224:225], off
	v_lshl_add_u64 v[224:225], s[36:37], 0, v[162:163]
	s_mov_b32 m0, s29
	s_nop 0
	global_load_lds_dwordx4 v[224:225], off
	s_mov_b32 m0, s64
	s_nop 0
	global_load_lds_dwordx4 v[226:227], off
	s_waitcnt vmcnt(8)
	s_waitcnt lgkmcnt(0)
	s_barrier
; #define PG8_STAGE(bufoff, gbase, voff) do { _Pragma("unroll") for (int _i = 0; _i < 2; ++_i) \
;         __builtin_amdgcn_global_load_lds((const unsigned*)((const char*)(gbase) + (voff)[_i]), (PG8_LAS unsigned*)(lds + (bufoff) + ldsw + _i * 8192), 16, 0, 0); } while (0)
; #define PG8_LDA(dst, b, h) do { _Pragma("unroll") for (int m = 0; m < 4; ++m) _Pragma("unroll") for (int k = 0; k < 2; ++k) dst[m][k] = *(const PG8_LAS bf16x8*)(lds + PG8_SA(b, h) + aoff + m * 2048 + k * 1024); } while (0)
; #define PG8_LDB(dst, b, h) do { _Pragma("unroll") for (int n = 0; n < 2; ++n) _Pragma("unroll") for (int k = 0; k < 2; ++k) dst[n][k] = *(const PG8_LAS bf16x8*)(lds + PG8_SB(b, h) + boff + n * 2048 + k * 1024); } while (0)
; #define PG8_MMA(ai, bj, At, Bt) do { __builtin_amdgcn_s_setprio(1); _Pragma("unroll") for (int m = 0; m < 4; ++m) _Pragma("unroll") for (int n = 0; n < 2; ++n) _Pragma("unroll") for (int k = 0; k < 2; ++k) \
;         acc[ai][bj][m][n] = __builtin_amdgcn_mfma_f32_16x16x32_bf16(Bt[n][k], At[m][k], acc[ai][bj][m][n], 0, 0, 0); __builtin_amdgcn_s_setprio(0); } while (0)
; #define PG8_WAIT_V(n) asm volatile("s_waitcnt vmcnt(" #n ")" ::: "memory")
; #define PG8_WAIT_L(n) asm volatile("s_waitcnt lgkmcnt(" #n ")" ::: "memory")
; #define PG8_BAR __builtin_amdgcn_s_barrier()
; #define PG8_SCHED __builtin_amdgcn_sched_barrier(0)
; template <class Epi, class Sched, bool ALIGN_EPI = false, bool SP2 = false>
; __device__ __forceinline__ void gemm_phase(PG8_LAS unsigned char* lds, const Gemm g, const Sched& S, const Epi& E, int wid_in) {
;     ...
;             PG8_WAIT_V(8); PG8_WAIT_L(0); PG8_BAR; PG8_MMA(1, 0, At, B0); PG8_MMA(1, 1, At, B1); PG8_BAR; PG8_SCHED;
;             PG8_LDB(B0, 1, 0); PG8_LDB(B1, 1, 1); PG8_SCHED; PG8_LDA(At, 1, 0); PG8_STAGE(PG8_SA(0, 1), a2 + hstep, voffA);
;             PG8_WAIT_V(8); PG8_WAIT_L(0); PG8_BAR; PG8_MMA(0, 0, At, B0); PG8_MMA(0, 1, At, B1); PG8_BAR; PG8_SCHED;
	v_mfma_f32_16x16x32_bf16 v[62:65], v[130:133], v[172:175], v[62:65]
	v_mfma_f32_16x16x32_bf16 v[58:61], v[138:141], v[172:175], v[58:61]
	v_mfma_f32_16x16x32_bf16 v[54:57], v[130:133], v[180:183], v[54:57]
	v_mfma_f32_16x16x32_bf16 v[50:53], v[138:141], v[180:183], v[50:53]
	v_mfma_f32_16x16x32_bf16 v[38:41], v[130:133], v[190:193], v[38:41]
	v_mfma_f32_16x16x32_bf16 v[34:37], v[138:141], v[190:193], v[34:37]
	v_mfma_f32_16x16x32_bf16 v[22:25], v[130:133], v[212:215], v[22:25]
	v_mfma_f32_16x16x32_bf16 v[18:21], v[138:141], v[212:215], v[18:21]
	v_mfma_f32_16x16x32_bf16 v[62:65], v[134:137], v[176:179], v[62:65]
	v_mfma_f32_16x16x32_bf16 v[58:61], v[142:145], v[176:179], v[58:61]
	v_mfma_f32_16x16x32_bf16 v[54:57], v[134:137], v[184:187], v[54:57]
	v_mfma_f32_16x16x32_bf16 v[50:53], v[142:145], v[184:187], v[50:53]
	v_mfma_f32_16x16x32_bf16 v[38:41], v[134:137], v[208:211], v[38:41]
	v_mfma_f32_16x16x32_bf16 v[34:37], v[142:145], v[208:211], v[34:37]
	v_mfma_f32_16x16x32_bf16 v[22:25], v[134:137], v[216:219], v[22:25]
	v_mfma_f32_16x16x32_bf16 v[18:21], v[142:145], v[216:219], v[18:21]
	v_mfma_f32_16x16x32_bf16 v[46:49], v[146:149], v[172:175], v[46:49]
	v_mfma_f32_16x16x32_bf16 v[42:45], v[154:157], v[172:175], v[42:45]
	v_mfma_f32_16x16x32_bf16 v[30:33], v[146:149], v[180:183], v[30:33]
	v_mfma_f32_16x16x32_bf16 v[26:29], v[154:157], v[180:183], v[26:29]
	v_mfma_f32_16x16x32_bf16 v[14:17], v[146:149], v[190:193], v[14:17]
	v_mfma_f32_16x16x32_bf16 v[10:13], v[154:157], v[190:193], v[10:13]
	v_mfma_f32_16x16x32_bf16 v[6:9], v[146:149], v[212:215], v[6:9]
	v_mfma_f32_16x16x32_bf16 v[2:5], v[154:157], v[212:215], v[2:5]
	v_mfma_f32_16x16x32_bf16 v[46:49], v[150:153], v[176:179], v[46:49]
	v_mfma_f32_16x16x32_bf16 v[42:45], v[158:161], v[176:179], v[42:45]
	v_mfma_f32_16x16x32_bf16 v[30:33], v[150:153], v[184:187], v[30:33]
	v_mfma_f32_16x16x32_bf16 v[26:29], v[158:161], v[184:187], v[26:29]
	v_mfma_f32_16x16x32_bf16 v[14:17], v[150:153], v[208:211], v[14:17]
	v_mfma_f32_16x16x32_bf16 v[10:13], v[158:161], v[208:211], v[10:13]
	v_mfma_f32_16x16x32_bf16 v[6:9], v[150:153], v[216:219], v[6:9]
	v_mfma_f32_16x16x32_bf16 v[2:5], v[158:161], v[216:219], v[2:5]
	s_barrier
	s_add_i32 s40, 0, 0x18000
	s_add_i32 s41, 0, 0x1c000
	v_add_u32_e32 v142, s40, v188
	v_add_u32_e32 v158, s41, v188
	ds_read_b128 v[130:133], v142
	ds_read_b128 v[134:137], v142 offset:1024
	ds_read_b128 v[138:141], v142 offset:2048
	ds_read_b128 v[142:145], v142 offset:3072
	ds_read_b128 v[146:149], v158
	ds_read_b128 v[150:153], v158 offset:1024
	ds_read_b128 v[154:157], v158 offset:2048
	ds_read_b128 v[158:161], v158 offset:3072
	s_add_u32 s36, s36, 0x40000
	s_addc_u32 s37, s37, 0
	s_mov_b32 m0, s65
	v_lshl_add_u64 v[228:229], s[36:37], 0, v[162:163]
	ds_read_b128 v[172:175], v189 offset:32768
	ds_read_b128 v[176:179], v189 offset:33792
	ds_read_b128 v[180:183], v189 offset:34816
	ds_read_b128 v[184:187], v189 offset:35840
	ds_read_b128 v[190:193], v189 offset:36864
	ds_read_b128 v[208:211], v189 offset:37888
	ds_read_b128 v[212:215], v189 offset:38912
	ds_read_b128 v[216:219], v189 offset:39936
	global_load_lds_dwordx4 v[228:229], off
	v_lshl_add_u64 v[228:229], s[36:37], 0, v[164:165]
	s_mov_b32 m0, s62
	s_nop 0
	global_load_lds_dwordx4 v[228:229], off
	s_waitcnt vmcnt(8)
	s_waitcnt lgkmcnt(0)
	s_barrier
	v_mfma_f32_16x16x32_bf16 v[126:129], v[130:133], v[172:175], v[126:129]
	v_mfma_f32_16x16x32_bf16 v[122:125], v[138:141], v[172:175], v[122:125]
	v_mfma_f32_16x16x32_bf16 v[118:121], v[130:133], v[180:183], v[118:121]
	v_mfma_f32_16x16x32_bf16 v[114:117], v[138:141], v[180:183], v[114:117]
	v_mfma_f32_16x16x32_bf16 v[102:105], v[130:133], v[190:193], v[102:105]
	v_mfma_f32_16x16x32_bf16 v[98:101], v[138:141], v[190:193], v[98:101]
	v_mfma_f32_16x16x32_bf16 v[86:89], v[130:133], v[212:215], v[86:89]
	v_mfma_f32_16x16x32_bf16 v[82:85], v[138:141], v[212:215], v[82:85]
	v_mfma_f32_16x16x32_bf16 v[126:129], v[134:137], v[176:179], v[126:129]
	v_mfma_f32_16x16x32_bf16 v[122:125], v[142:145], v[176:179], v[122:125]
	v_mfma_f32_16x16x32_bf16 v[118:121], v[134:137], v[184:187], v[118:121]
	v_mfma_f32_16x16x32_bf16 v[114:117], v[142:145], v[184:187], v[114:117]
	v_mfma_f32_16x16x32_bf16 v[102:105], v[134:137], v[208:211], v[102:105]
	v_mfma_f32_16x16x32_bf16 v[98:101], v[142:145], v[208:211], v[98:101]
	v_mfma_f32_16x16x32_bf16 v[86:89], v[134:137], v[216:219], v[86:89]
	v_mfma_f32_16x16x32_bf16 v[82:85], v[142:145], v[216:219], v[82:85]
	v_mfma_f32_16x16x32_bf16 v[110:113], v[146:149], v[172:175], v[110:113]
	v_mfma_f32_16x16x32_bf16 v[106:109], v[154:157], v[172:175], v[106:109]
	v_mfma_f32_16x16x32_bf16 v[94:97], v[146:149], v[180:183], v[94:97]
	v_mfma_f32_16x16x32_bf16 v[90:93], v[154:157], v[180:183], v[90:93]
	v_mfma_f32_16x16x32_bf16 v[78:81], v[146:149], v[190:193], v[78:81]
	v_mfma_f32_16x16x32_bf16 v[74:77], v[154:157], v[190:193], v[74:77]
	v_mfma_f32_16x16x32_bf16 v[70:73], v[146:149], v[212:215], v[70:73]
	v_mfma_f32_16x16x32_bf16 v[66:69], v[154:157], v[212:215], v[66:69]
	v_mfma_f32_16x16x32_bf16 v[110:113], v[150:153], v[176:179], v[110:113]
	v_mfma_f32_16x16x32_bf16 v[106:109], v[158:161], v[176:179], v[106:109]
	v_mfma_f32_16x16x32_bf16 v[94:97], v[150:153], v[184:187], v[94:97]
	v_mfma_f32_16x16x32_bf16 v[90:93], v[158:161], v[184:187], v[90:93]
	v_mfma_f32_16x16x32_bf16 v[78:81], v[150:153], v[208:211], v[78:81]
	v_mfma_f32_16x16x32_bf16 v[74:77], v[158:161], v[208:211], v[74:77]
	v_mfma_f32_16x16x32_bf16 v[70:73], v[150:153], v[216:219], v[70:73]
	v_mfma_f32_16x16x32_bf16 v[66:69], v[158:161], v[216:219], v[66:69]
	s_barrier
; #define PG8_STAGE(bufoff, gbase, voff) do { _Pragma("unroll") for (int _i = 0; _i < 2; ++_i) \
;         __builtin_amdgcn_global_load_lds((const unsigned*)((const char*)(gbase) + (voff)[_i]), (PG8_LAS unsigned*)(lds + (bufoff) + ldsw + _i * 8192), 16, 0, 0); } while (0)
; #define PG8_LDA(dst, b, h) do { _Pragma("unroll") for (int m = 0; m < 4; ++m) _Pragma("unroll") for (int k = 0; k < 2; ++k) dst[m][k] = *(const PG8_LAS bf16x8*)(lds + PG8_SA(b, h) + aoff + m * 2048 + k * 1024); } while (0)
; #define PG8_MMA(ai, bj, At, Bt) do { __builtin_amdgcn_s_setprio(1); _Pragma("unroll") for (int m = 0; m < 4; ++m) _Pragma("unroll") for (int n = 0; n < 2; ++n) _Pragma("unroll") for (int k = 0; k < 2; ++k) \
;         acc[ai][bj][m][n] = __builtin_amdgcn_mfma_f32_16x16x32_bf16(Bt[n][k], At[m][k], acc[ai][bj][m][n], 0, 0, 0); __builtin_amdgcn_s_setprio(0); } while (0)
; #define PG8_WAIT_V(n) asm volatile("s_waitcnt vmcnt(" #n ")" ::: "memory")
; #define PG8_WAIT_L(n) asm volatile("s_waitcnt lgkmcnt(" #n ")" ::: "memory")
; #define PG8_BAR __builtin_amdgcn_s_barrier()
; #define PG8_SCHED __builtin_amdgcn_sched_barrier(0)
; template <class Epi, class Sched, bool ALIGN_EPI = false, bool SP2 = false>
; __device__ __forceinline__ void gemm_phase(PG8_LAS unsigned char* lds, const Gemm g, const Sched& S, const Epi& E, int wid_in) {
;     ...
;             PG8_LDA(At, 1, 1); PG8_STAGE(PG8_SB(1, 0), b3, voffB); PG8_STAGE(PG8_SB(1, 1), b3 + hstep, voffB); PG8_STAGE(PG8_SA(1, 0), a3, voffA);
;             PG8_WAIT_V(8); PG8_WAIT_L(0); PG8_BAR; PG8_MMA(1, 0, At, B0); PG8_MMA(1, 1, At, B1); PG8_BAR; PG8_SCHED;
;     ...
;         if constexpr (ALIGN_EPI) { if (wr == 0) PG8_BAR; }
	s_add_i32 s36, s40, s59
	v_lshl_add_u64 v[220:221], v[220:221], 0, s[94:95]
	s_mov_b32 m0, s36
	ds_read_b128 v[172:175], v189 offset:49152
	ds_read_b128 v[176:179], v189 offset:50176
	ds_read_b128 v[180:183], v189 offset:51200
	ds_read_b128 v[184:187], v189 offset:52224
	ds_read_b128 v[190:193], v189 offset:53248
	ds_read_b128 v[208:211], v189 offset:54272
	ds_read_b128 v[212:215], v189 offset:55296
	ds_read_b128 v[216:219], v189 offset:56320
	global_load_lds_dwordx4 v[220:221], off
	s_add_i32 m0, s36, 0x2000
	s_add_u32 s34, s34, 0x40080
	v_lshl_add_u64 v[220:221], v[222:223], 0, s[94:95]
	s_addc_u32 s35, s35, 0
	s_add_i32 s36, s41, s59
	global_load_lds_dwordx4 v[220:221], off
	v_lshl_add_u64 v[220:221], s[34:35], 0, v[0:1]
	s_mov_b32 m0, s36
	s_nop 0
	global_load_lds_dwordx4 v[220:221], off
	v_lshl_add_u64 v[220:221], s[34:35], 0, v[166:167]
	s_add_i32 m0, s36, 0x2000
	s_nop 0
	global_load_lds_dwordx4 v[220:221], off
	v_lshl_add_u64 v[220:221], v[224:225], 0, s[94:95]
	s_mov_b32 m0, s88
	s_nop 0
	global_load_lds_dwordx4 v[220:221], off
	v_lshl_add_u64 v[220:221], v[226:227], 0, s[94:95]
	s_mov_b32 m0, s89
	s_nop 0
	global_load_lds_dwordx4 v[220:221], off
	s_waitcnt vmcnt(8)
	s_waitcnt lgkmcnt(0)
	s_barrier
	v_mfma_f32_16x16x32_bf16 v[62:65], v[130:133], v[172:175], v[62:65]
	v_mfma_f32_16x16x32_bf16 v[58:61], v[138:141], v[172:175], v[58:61]
	v_mfma_f32_16x16x32_bf16 v[54:57], v[130:133], v[180:183], v[54:57]
	v_mfma_f32_16x16x32_bf16 v[50:53], v[138:141], v[180:183], v[50:53]
	v_mfma_f32_16x16x32_bf16 v[38:41], v[130:133], v[190:193], v[38:41]
	v_mfma_f32_16x16x32_bf16 v[34:37], v[138:141], v[190:193], v[34:37]
	v_mfma_f32_16x16x32_bf16 v[22:25], v[130:133], v[212:215], v[22:25]
	v_mfma_f32_16x16x32_bf16 v[18:21], v[138:141], v[212:215], v[18:21]
	v_mfma_f32_16x16x32_bf16 v[62:65], v[134:137], v[176:179], v[62:65]
	v_mfma_f32_16x16x32_bf16 v[58:61], v[142:145], v[176:179], v[58:61]
	v_mfma_f32_16x16x32_bf16 v[54:57], v[134:137], v[184:187], v[54:57]
	v_mfma_f32_16x16x32_bf16 v[50:53], v[142:145], v[184:187], v[50:53]
	v_mfma_f32_16x16x32_bf16 v[38:41], v[134:137], v[208:211], v[38:41]
	v_mfma_f32_16x16x32_bf16 v[34:37], v[142:145], v[208:211], v[34:37]
	v_mfma_f32_16x16x32_bf16 v[22:25], v[134:137], v[216:219], v[22:25]
	v_mfma_f32_16x16x32_bf16 v[18:21], v[142:145], v[216:219], v[18:21]
	v_mfma_f32_16x16x32_bf16 v[46:49], v[146:149], v[172:175], v[46:49]
	v_mfma_f32_16x16x32_bf16 v[42:45], v[154:157], v[172:175], v[42:45]
	v_mfma_f32_16x16x32_bf16 v[30:33], v[146:149], v[180:183], v[30:33]
	v_mfma_f32_16x16x32_bf16 v[26:29], v[154:157], v[180:183], v[26:29]
	v_mfma_f32_16x16x32_bf16 v[14:17], v[146:149], v[190:193], v[14:17]
	v_mfma_f32_16x16x32_bf16 v[10:13], v[154:157], v[190:193], v[10:13]
	v_mfma_f32_16x16x32_bf16 v[6:9], v[146:149], v[212:215], v[6:9]
	v_mfma_f32_16x16x32_bf16 v[2:5], v[154:157], v[212:215], v[2:5]
	v_mfma_f32_16x16x32_bf16 v[46:49], v[150:153], v[176:179], v[46:49]
	v_mfma_f32_16x16x32_bf16 v[42:45], v[158:161], v[176:179], v[42:45]
	v_mfma_f32_16x16x32_bf16 v[30:33], v[150:153], v[184:187], v[30:33]
	v_mfma_f32_16x16x32_bf16 v[26:29], v[158:161], v[184:187], v[26:29]
	v_mfma_f32_16x16x32_bf16 v[14:17], v[150:153], v[208:211], v[14:17]
	v_mfma_f32_16x16x32_bf16 v[10:13], v[158:161], v[208:211], v[10:13]
	v_mfma_f32_16x16x32_bf16 v[6:9], v[150:153], v[216:219], v[6:9]
	v_mfma_f32_16x16x32_bf16 v[2:5], v[158:161], v[216:219], v[2:5]
	s_barrier
	s_add_u32 vcc_hi, vcc_hi, 0x100
	s_addc_u32 s63, s63, 0
	s_add_u32 s30, s30, 0x100
	s_addc_u32 s31, s31, 0
	s_cmp_ge_i32 s56, s1
	s_mov_b32 s34, s56
	s_cbranch_scc0 .LBB0_848
	s_setprio 0
	s_and_b64 vcc, exec, s[12:13]
	s_cbranch_vccz .LBB0_851
	s_barrier

; #define PG8_STAGE(bufoff, gbase, voff) do { _Pragma("unroll") for (int _i = 0; _i < 2; ++_i) \
;         __builtin_amdgcn_global_load_lds((const unsigned*)((const char*)(gbase) + (voff)[_i]), (PG8_LAS unsigned*)(lds + (bufoff) + ldsw + _i * 8192), 16, 0, 0); } while (0)
; #define PG8_LDA(dst, b, h) do { _Pragma("unroll") for (int m = 0; m < 4; ++m) _Pragma("unroll") for (int k = 0; k < 2; ++k) dst[m][k] = *(const PG8_LAS bf16x8*)(lds + PG8_SA(b, h) + aoff + m * 2048 + k * 1024); } while (0)
; #define PG8_LDB(dst, b, h) do { _Pragma("unroll") for (int n = 0; n < 2; ++n) _Pragma("unroll") for (int k = 0; k < 2; ++k) dst[n][k] = *(const PG8_LAS bf16x8*)(lds + PG8_SB(b, h) + boff + n * 2048 + k * 1024); } while (0)
; #define PG8_MMA(ai, bj, At, Bt) do { __builtin_amdgcn_s_setprio(1); _Pragma("unroll") for (int m = 0; m < 4; ++m) _Pragma("unroll") for (int n = 0; n < 2; ++n) _Pragma("unroll") for (int k = 0; k < 2; ++k) \
;         acc[ai][bj][m][n] = __builtin_amdgcn_mfma_f32_16x16x32_bf16(Bt[n][k], At[m][k], acc[ai][bj][m][n], 0, 0, 0); __builtin_amdgcn_s_setprio(0); } while (0)
; #define PG8_WAIT_V(n) asm volatile("s_waitcnt vmcnt(" #n ")" ::: "memory")
; #define PG8_BAR __builtin_amdgcn_s_barrier()
; template <class Epi, class Sched, bool ALIGN_EPI = false, bool SP2 = false>
; __device__ __forceinline__ void gemm_phase(PG8_LAS unsigned char* lds, const Gemm g, const Sched& S, const Epi& E, int wid_in) {
;     ...
;         for (int t = 0; t < nt; t += 2) {
;             const bool last = (t == nt - 2);
;             const char* a1 = cA + (size_t)(t + 1) * kstep;
;             const char* a2 = last ? nA : cA + (size_t)(t + 2) * kstep; const char* b2 = last ? nB : cB + (size_t)(t + 2) * kstep;
;             const char* a3 = a2 + kstep; const char* b3 = b2 + kstep;
;             if (last && has_next) S.a_ready(nxt);
;             if constexpr (SP2) {
;             PG8_LDB(B0, 0, 0); PG8_LDB(B1, 0, 1); PG8_SCHED; PG8_LDA(At, 0, 0); PG8_STAGE(PG8_SA(1, 1), a1 + hstep, voffA);
;             PG8_WAIT_V(8); PG8_WAIT_L(0); PG8_BAR; PG8_MMA(0, 0, At, B0); PG8_MMA(0, 1, At, B1); PG8_BAR; PG8_SCHED;
;             PG8_LDA(At, 0, 1); PG8_STAGE(PG8_SB(0, 0), b2, voffB); PG8_STAGE(PG8_SB(0, 1), b2 + hstep, voffB); PG8_STAGE(PG8_SA(0, 0), a2, voffA);
;             PG8_WAIT_V(8); PG8_WAIT_L(0); PG8_BAR; PG8_MMA(1, 0, At, B0); PG8_MMA(1, 1, At, B1); PG8_BAR; PG8_SCHED;
.Lprio_skip_2:
.LBB0_880:
	s_add_i32 s56, s34, 2
	s_add_u32 s35, s30, 0xfffc0080
	s_addc_u32 s36, s31, -1
	s_add_i32 s40, 0, 0x10000
	s_cmp_eq_u32 vcc_lo, s34
	s_cselect_b32 s37, s15, s36
	s_cselect_b32 s36, s19, s35
	s_cselect_b32 s35, s17, s63
	s_cselect_b32 s34, s27, vcc_hi
	s_add_i32 s42, 0, 0x14000
	v_add_u32_e32 v142, s40, v195
	v_add_u32_e32 v158, s42, v195
	ds_read_b128 v[130:133], v142
	ds_read_b128 v[134:137], v142 offset:1024
	ds_read_b128 v[138:141], v142 offset:2048
	ds_read_b128 v[142:145], v142 offset:3072
	ds_read_b128 v[146:149], v158
	ds_read_b128 v[150:153], v158 offset:1024
	ds_read_b128 v[154:157], v158 offset:2048
	ds_read_b128 v[158:161], v158 offset:3072
	v_lshl_add_u64 v[218:219], s[30:31], 0, v[216:217]
	s_add_i32 m0, s29, 0xc000
	ds_read_b128 v[162:165], v251
	ds_read_b128 v[166:169], v251 offset:1024
	ds_read_b128 v[170:173], v251 offset:2048
	ds_read_b128 v[174:177], v251 offset:3072
	ds_read_b128 v[178:181], v251 offset:4096
	ds_read_b128 v[182:185], v251 offset:5120
	ds_read_b128 v[186:189], v251 offset:6144
	ds_read_b128 v[190:193], v251 offset:7168
	global_load_lds_dwordx4 v[218:219], off
	v_lshl_add_u64 v[218:219], s[30:31], 0, v[214:215]
	s_add_i32 m0, s29, 0xe000
	s_nop 0
	global_load_lds_dwordx4 v[218:219], off
	s_waitcnt vmcnt(8)
	s_waitcnt lgkmcnt(0)
	s_barrier
	v_mfma_f32_16x16x32_bf16 v[126:129], v[130:133], v[162:165], v[126:129]
	v_mfma_f32_16x16x32_bf16 v[122:125], v[138:141], v[162:165], v[122:125]
	v_mfma_f32_16x16x32_bf16 v[118:121], v[130:133], v[170:173], v[118:121]
	v_mfma_f32_16x16x32_bf16 v[114:117], v[138:141], v[170:173], v[114:117]
	v_mfma_f32_16x16x32_bf16 v[102:105], v[130:133], v[178:181], v[102:105]
	v_mfma_f32_16x16x32_bf16 v[98:101], v[138:141], v[178:181], v[98:101]
	v_mfma_f32_16x16x32_bf16 v[86:89], v[130:133], v[186:189], v[86:89]
	v_mfma_f32_16x16x32_bf16 v[82:85], v[138:141], v[186:189], v[82:85]
	v_mfma_f32_16x16x32_bf16 v[126:129], v[134:137], v[166:169], v[126:129]
	v_mfma_f32_16x16x32_bf16 v[122:125], v[142:145], v[166:169], v[122:125]
	v_mfma_f32_16x16x32_bf16 v[118:121], v[134:137], v[174:177], v[118:121]
	v_mfma_f32_16x16x32_bf16 v[114:117], v[142:145], v[174:177], v[114:117]
	v_mfma_f32_16x16x32_bf16 v[102:105], v[134:137], v[182:185], v[102:105]
	v_mfma_f32_16x16x32_bf16 v[98:101], v[142:145], v[182:185], v[98:101]
	v_mfma_f32_16x16x32_bf16 v[86:89], v[134:137], v[190:193], v[86:89]
	v_mfma_f32_16x16x32_bf16 v[82:85], v[142:145], v[190:193], v[82:85]
	v_mfma_f32_16x16x32_bf16 v[110:113], v[146:149], v[162:165], v[110:113]
	v_mfma_f32_16x16x32_bf16 v[106:109], v[154:157], v[162:165], v[106:109]
	v_mfma_f32_16x16x32_bf16 v[94:97], v[146:149], v[170:173], v[94:97]
	v_mfma_f32_16x16x32_bf16 v[90:93], v[154:157], v[170:173], v[90:93]
	v_mfma_f32_16x16x32_bf16 v[78:81], v[146:149], v[178:181], v[78:81]
	v_mfma_f32_16x16x32_bf16 v[74:77], v[154:157], v[178:181], v[74:77]
	v_mfma_f32_16x16x32_bf16 v[70:73], v[146:149], v[186:189], v[70:73]
	v_mfma_f32_16x16x32_bf16 v[66:69], v[154:157], v[186:189], v[66:69]
	v_mfma_f32_16x16x32_bf16 v[110:113], v[150:153], v[166:169], v[110:113]
	v_mfma_f32_16x16x32_bf16 v[106:109], v[158:161], v[166:169], v[106:109]
	v_mfma_f32_16x16x32_bf16 v[94:97], v[150:153], v[174:177], v[94:97]
	v_mfma_f32_16x16x32_bf16 v[90:93], v[158:161], v[174:177], v[90:93]
	v_mfma_f32_16x16x32_bf16 v[78:81], v[150:153], v[182:185], v[78:81]
	v_mfma_f32_16x16x32_bf16 v[74:77], v[158:161], v[182:185], v[74:77]
	v_mfma_f32_16x16x32_bf16 v[70:73], v[150:153], v[190:193], v[70:73]
	v_mfma_f32_16x16x32_bf16 v[66:69], v[158:161], v[190:193], v[66:69]
	s_barrier
	s_add_i32 s40, s40, s59
	v_lshl_add_u64 v[218:219], s[34:35], 0, v[0:1]
	s_mov_b32 m0, s40
	ds_read_b128 v[162:165], v251 offset:16384
	ds_read_b128 v[166:169], v251 offset:17408
	ds_read_b128 v[170:173], v251 offset:18432
	ds_read_b128 v[174:177], v251 offset:19456
	ds_read_b128 v[178:181], v251 offset:20480
	ds_read_b128 v[182:185], v251 offset:21504
	ds_read_b128 v[186:189], v251 offset:22528
	ds_read_b128 v[190:193], v251 offset:23552
	global_load_lds_dwordx4 v[218:219], off
	s_add_i32 m0, s40, 0x2000
	s_add_u32 s40, s34, 0x40000
	v_lshl_add_u64 v[220:221], s[34:35], 0, v[212:213]
	s_addc_u32 s41, s35, 0
	s_add_i32 s42, s42, s59
	global_load_lds_dwordx4 v[220:221], off
	v_lshl_add_u64 v[222:223], s[40:41], 0, v[0:1]
	s_mov_b32 m0, s42
	v_lshl_add_u64 v[224:225], s[36:37], 0, v[210:211]
	global_load_lds_dwordx4 v[222:223], off
	v_lshl_add_u64 v[222:223], s[40:41], 0, v[212:213]
	s_add_i32 m0, s42, 0x2000
	s_nop 0
	global_load_lds_dwordx4 v[222:223], off
	v_lshl_add_u64 v[222:223], s[36:37], 0, v[208:209]
	s_mov_b32 m0, s29
	s_nop 0
	global_load_lds_dwordx4 v[222:223], off
	s_mov_b32 m0, s48
	s_nop 0
	global_load_lds_dwordx4 v[224:225], off
	s_waitcnt vmcnt(8)
	s_waitcnt lgkmcnt(0)
	s_barrier
; #define PG8_STAGE(bufoff, gbase, voff) do { _Pragma("unroll") for (int _i = 0; _i < 2; ++_i) \
;         __builtin_amdgcn_global_load_lds((const unsigned*)((const char*)(gbase) + (voff)[_i]), (PG8_LAS unsigned*)(lds + (bufoff) + ldsw + _i * 8192), 16, 0, 0); } while (0)
; #define PG8_LDA(dst, b, h) do { _Pragma("unroll") for (int m = 0; m < 4; ++m) _Pragma("unroll") for (int k = 0; k < 2; ++k) dst[m][k] = *(const PG8_LAS bf16x8*)(lds + PG8_SA(b, h) + aoff + m * 2048 + k * 1024); } while (0)
; #define PG8_LDB(dst, b, h) do { _Pragma("unroll") for (int n = 0; n < 2; ++n) _Pragma("unroll") for (int k = 0; k < 2; ++k) dst[n][k] = *(const PG8_LAS bf16x8*)(lds + PG8_SB(b, h) + boff + n * 2048 + k * 1024); } while (0)
; #define PG8_MMA(ai, bj, At, Bt) do { __builtin_amdgcn_s_setprio(1); _Pragma("unroll") for (int m = 0; m < 4; ++m) _Pragma("unroll") for (int n = 0; n < 2; ++n) _Pragma("unroll") for (int k = 0; k < 2; ++k) \
;         acc[ai][bj][m][n] = __builtin_amdgcn_mfma_f32_16x16x32_bf16(Bt[n][k], At[m][k], acc[ai][bj][m][n], 0, 0, 0); __builtin_amdgcn_s_setprio(0); } while (0)
; #define PG8_WAIT_V(n) asm volatile("s_waitcnt vmcnt(" #n ")" ::: "memory")
; #define PG8_WAIT_L(n) asm volatile("s_waitcnt lgkmcnt(" #n ")" ::: "memory")
; #define PG8_BAR __builtin_amdgcn_s_barrier()
; #define PG8_SCHED __builtin_amdgcn_sched_barrier(0)
; template <class Epi, class Sched, bool ALIGN_EPI = false, bool SP2 = false>
; __device__ __forceinline__ void gemm_phase(PG8_LAS unsigned char* lds, const Gemm g, const Sched& S, const Epi& E, int wid_in) {
;     ...
;             PG8_WAIT_V(8); PG8_WAIT_L(0); PG8_BAR; PG8_MMA(1, 0, At, B0); PG8_MMA(1, 1, At, B1); PG8_BAR; PG8_SCHED;
;             PG8_LDB(B0, 1, 0); PG8_LDB(B1, 1, 1); PG8_SCHED; PG8_LDA(At, 1, 0); PG8_STAGE(PG8_SA(0, 1), a2 + hstep, voffA);
;             PG8_WAIT_V(8); PG8_WAIT_L(0); PG8_BAR; PG8_MMA(0, 0, At, B0); PG8_MMA(0, 1, At, B1); PG8_BAR; PG8_SCHED;
	v_mfma_f32_16x16x32_bf16 v[62:65], v[130:133], v[162:165], v[62:65]
	v_mfma_f32_16x16x32_bf16 v[58:61], v[138:141], v[162:165], v[58:61]
	v_mfma_f32_16x16x32_bf16 v[54:57], v[130:133], v[170:173], v[54:57]
	v_mfma_f32_16x16x32_bf16 v[50:53], v[138:141], v[170:173], v[50:53]
	v_mfma_f32_16x16x32_bf16 v[38:41], v[130:133], v[178:181], v[38:41]
	v_mfma_f32_16x16x32_bf16 v[34:37], v[138:141], v[178:181], v[34:37]
	v_mfma_f32_16x16x32_bf16 v[22:25], v[130:133], v[186:189], v[22:25]
	v_mfma_f32_16x16x32_bf16 v[18:21], v[138:141], v[186:189], v[18:21]
	v_mfma_f32_16x16x32_bf16 v[62:65], v[134:137], v[166:169], v[62:65]
	v_mfma_f32_16x16x32_bf16 v[58:61], v[142:145], v[166:169], v[58:61]
	v_mfma_f32_16x16x32_bf16 v[54:57], v[134:137], v[174:177], v[54:57]
	v_mfma_f32_16x16x32_bf16 v[50:53], v[142:145], v[174:177], v[50:53]
	v_mfma_f32_16x16x32_bf16 v[38:41], v[134:137], v[182:185], v[38:41]
	v_mfma_f32_16x16x32_bf16 v[34:37], v[142:145], v[182:185], v[34:37]
	v_mfma_f32_16x16x32_bf16 v[22:25], v[134:137], v[190:193], v[22:25]
	v_mfma_f32_16x16x32_bf16 v[18:21], v[142:145], v[190:193], v[18:21]
	v_mfma_f32_16x16x32_bf16 v[46:49], v[146:149], v[162:165], v[46:49]
	v_mfma_f32_16x16x32_bf16 v[42:45], v[154:157], v[162:165], v[42:45]
	v_mfma_f32_16x16x32_bf16 v[30:33], v[146:149], v[170:173], v[30:33]
	v_mfma_f32_16x16x32_bf16 v[26:29], v[154:157], v[170:173], v[26:29]
	v_mfma_f32_16x16x32_bf16 v[14:17], v[146:149], v[178:181], v[14:17]
	v_mfma_f32_16x16x32_bf16 v[10:13], v[154:157], v[178:181], v[10:13]
	v_mfma_f32_16x16x32_bf16 v[6:9], v[146:149], v[186:189], v[6:9]
	v_mfma_f32_16x16x32_bf16 v[2:5], v[154:157], v[186:189], v[2:5]
	v_mfma_f32_16x16x32_bf16 v[46:49], v[150:153], v[166:169], v[46:49]
	v_mfma_f32_16x16x32_bf16 v[42:45], v[158:161], v[166:169], v[42:45]
	v_mfma_f32_16x16x32_bf16 v[30:33], v[150:153], v[174:177], v[30:33]
	v_mfma_f32_16x16x32_bf16 v[26:29], v[158:161], v[174:177], v[26:29]
	v_mfma_f32_16x16x32_bf16 v[14:17], v[150:153], v[182:185], v[14:17]
	v_mfma_f32_16x16x32_bf16 v[10:13], v[158:161], v[182:185], v[10:13]
	v_mfma_f32_16x16x32_bf16 v[6:9], v[150:153], v[190:193], v[6:9]
	v_mfma_f32_16x16x32_bf16 v[2:5], v[158:161], v[190:193], v[2:5]
	s_barrier
	s_add_i32 s40, 0, 0x18000
	s_add_i32 s41, 0, 0x1c000
	v_add_u32_e32 v142, s40, v195
	v_add_u32_e32 v158, s41, v195
	ds_read_b128 v[130:133], v142
	ds_read_b128 v[134:137], v142 offset:1024
	ds_read_b128 v[138:141], v142 offset:2048
	ds_read_b128 v[142:145], v142 offset:3072
	ds_read_b128 v[146:149], v158
	ds_read_b128 v[150:153], v158 offset:1024
	ds_read_b128 v[154:157], v158 offset:2048
	ds_read_b128 v[158:161], v158 offset:3072
	s_add_u32 s36, s36, 0x40000
	s_addc_u32 s37, s37, 0
	s_mov_b32 m0, s61
	v_lshl_add_u64 v[226:227], s[36:37], 0, v[208:209]
	ds_read_b128 v[162:165], v251 offset:32768
	ds_read_b128 v[166:169], v251 offset:33792
	ds_read_b128 v[170:173], v251 offset:34816
	ds_read_b128 v[174:177], v251 offset:35840
	ds_read_b128 v[178:181], v251 offset:36864
	ds_read_b128 v[182:185], v251 offset:37888
	ds_read_b128 v[186:189], v251 offset:38912
	ds_read_b128 v[190:193], v251 offset:39936
	global_load_lds_dwordx4 v[226:227], off
	v_lshl_add_u64 v[226:227], s[36:37], 0, v[210:211]
	s_mov_b32 m0, s62
	s_nop 0
	global_load_lds_dwordx4 v[226:227], off
	s_waitcnt vmcnt(8)
	s_waitcnt lgkmcnt(0)
	s_barrier
	v_mfma_f32_16x16x32_bf16 v[126:129], v[130:133], v[162:165], v[126:129]
	v_mfma_f32_16x16x32_bf16 v[122:125], v[138:141], v[162:165], v[122:125]
	v_mfma_f32_16x16x32_bf16 v[118:121], v[130:133], v[170:173], v[118:121]
	v_mfma_f32_16x16x32_bf16 v[114:117], v[138:141], v[170:173], v[114:117]
	v_mfma_f32_16x16x32_bf16 v[102:105], v[130:133], v[178:181], v[102:105]
	v_mfma_f32_16x16x32_bf16 v[98:101], v[138:141], v[178:181], v[98:101]
	v_mfma_f32_16x16x32_bf16 v[86:89], v[130:133], v[186:189], v[86:89]
	v_mfma_f32_16x16x32_bf16 v[82:85], v[138:141], v[186:189], v[82:85]
	v_mfma_f32_16x16x32_bf16 v[126:129], v[134:137], v[166:169], v[126:129]
	v_mfma_f32_16x16x32_bf16 v[122:125], v[142:145], v[166:169], v[122:125]
	v_mfma_f32_16x16x32_bf16 v[118:121], v[134:137], v[174:177], v[118:121]
	v_mfma_f32_16x16x32_bf16 v[114:117], v[142:145], v[174:177], v[114:117]
	v_mfma_f32_16x16x32_bf16 v[102:105], v[134:137], v[182:185], v[102:105]
	v_mfma_f32_16x16x32_bf16 v[98:101], v[142:145], v[182:185], v[98:101]
	v_mfma_f32_16x16x32_bf16 v[86:89], v[134:137], v[190:193], v[86:89]
	v_mfma_f32_16x16x32_bf16 v[82:85], v[142:145], v[190:193], v[82:85]
	v_mfma_f32_16x16x32_bf16 v[110:113], v[146:149], v[162:165], v[110:113]
	v_mfma_f32_16x16x32_bf16 v[106:109], v[154:157], v[162:165], v[106:109]
	v_mfma_f32_16x16x32_bf16 v[94:97], v[146:149], v[170:173], v[94:97]
	v_mfma_f32_16x16x32_bf16 v[90:93], v[154:157], v[170:173], v[90:93]
	v_mfma_f32_16x16x32_bf16 v[78:81], v[146:149], v[178:181], v[78:81]
	v_mfma_f32_16x16x32_bf16 v[74:77], v[154:157], v[178:181], v[74:77]
	v_mfma_f32_16x16x32_bf16 v[70:73], v[146:149], v[186:189], v[70:73]
	v_mfma_f32_16x16x32_bf16 v[66:69], v[154:157], v[186:189], v[66:69]
	v_mfma_f32_16x16x32_bf16 v[110:113], v[150:153], v[166:169], v[110:113]
	v_mfma_f32_16x16x32_bf16 v[106:109], v[158:161], v[166:169], v[106:109]
	v_mfma_f32_16x16x32_bf16 v[94:97], v[150:153], v[174:177], v[94:97]
	v_mfma_f32_16x16x32_bf16 v[90:93], v[158:161], v[174:177], v[90:93]
	v_mfma_f32_16x16x32_bf16 v[78:81], v[150:153], v[182:185], v[78:81]
	v_mfma_f32_16x16x32_bf16 v[74:77], v[158:161], v[182:185], v[74:77]
	v_mfma_f32_16x16x32_bf16 v[70:73], v[150:153], v[190:193], v[70:73]
	v_mfma_f32_16x16x32_bf16 v[66:69], v[158:161], v[190:193], v[66:69]
	s_barrier
; #define PG8_STAGE(bufoff, gbase, voff) do { _Pragma("unroll") for (int _i = 0; _i < 2; ++_i) \
;         __builtin_amdgcn_global_load_lds((const unsigned*)((const char*)(gbase) + (voff)[_i]), (PG8_LAS unsigned*)(lds + (bufoff) + ldsw + _i * 8192), 16, 0, 0); } while (0)
; #define PG8_LDA(dst, b, h) do { _Pragma("unroll") for (int m = 0; m < 4; ++m) _Pragma("unroll") for (int k = 0; k < 2; ++k) dst[m][k] = *(const PG8_LAS bf16x8*)(lds + PG8_SA(b, h) + aoff + m * 2048 + k * 1024); } while (0)
; #define PG8_MMA(ai, bj, At, Bt) do { __builtin_amdgcn_s_setprio(1); _Pragma("unroll") for (int m = 0; m < 4; ++m) _Pragma("unroll") for (int n = 0; n < 2; ++n) _Pragma("unroll") for (int k = 0; k < 2; ++k) \
;         acc[ai][bj][m][n] = __builtin_amdgcn_mfma_f32_16x16x32_bf16(Bt[n][k], At[m][k], acc[ai][bj][m][n], 0, 0, 0); __builtin_amdgcn_s_setprio(0); } while (0)
; #define PG8_WAIT_V(n) asm volatile("s_waitcnt vmcnt(" #n ")" ::: "memory")
; #define PG8_WAIT_L(n) asm volatile("s_waitcnt lgkmcnt(" #n ")" ::: "memory")
; #define PG8_BAR __builtin_amdgcn_s_barrier()
; #define PG8_SCHED __builtin_amdgcn_sched_barrier(0)
; template <class Epi, class Sched, bool ALIGN_EPI = false, bool SP2 = false>
; __device__ __forceinline__ void gemm_phase(PG8_LAS unsigned char* lds, const Gemm g, const Sched& S, const Epi& E, int wid_in) {
;     ...
;             PG8_LDA(At, 1, 1); PG8_STAGE(PG8_SB(1, 0), b3, voffB); PG8_STAGE(PG8_SB(1, 1), b3 + hstep, voffB); PG8_STAGE(PG8_SA(1, 0), a3, voffA);
;             PG8_WAIT_V(8); PG8_WAIT_L(0); PG8_BAR; PG8_MMA(1, 0, At, B0); PG8_MMA(1, 1, At, B1); PG8_BAR; PG8_SCHED;
;     ...
;         if constexpr (ALIGN_EPI) { if (wr == 0) PG8_BAR; }
	s_add_i32 s36, s40, s59
	v_lshl_add_u64 v[218:219], v[218:219], 0, s[94:95]
	s_mov_b32 m0, s36
	ds_read_b128 v[162:165], v251 offset:49152
	ds_read_b128 v[166:169], v251 offset:50176
	ds_read_b128 v[170:173], v251 offset:51200
	ds_read_b128 v[174:177], v251 offset:52224
	ds_read_b128 v[178:181], v251 offset:53248
	ds_read_b128 v[182:185], v251 offset:54272
	ds_read_b128 v[186:189], v251 offset:55296
	ds_read_b128 v[190:193], v251 offset:56320
	global_load_lds_dwordx4 v[218:219], off
	s_add_i32 m0, s36, 0x2000
	s_add_u32 s34, s34, 0x40080
	v_lshl_add_u64 v[218:219], v[220:221], 0, s[94:95]
	s_addc_u32 s35, s35, 0
	s_add_i32 s36, s41, s59
	global_load_lds_dwordx4 v[218:219], off
	v_lshl_add_u64 v[218:219], s[34:35], 0, v[0:1]
	s_mov_b32 m0, s36
	s_nop 0
	global_load_lds_dwordx4 v[218:219], off
	v_lshl_add_u64 v[218:219], s[34:35], 0, v[212:213]
	s_add_i32 m0, s36, 0x2000
	s_nop 0
	global_load_lds_dwordx4 v[218:219], off
	v_lshl_add_u64 v[218:219], v[222:223], 0, s[94:95]
	s_mov_b32 m0, s89
	s_nop 0
	global_load_lds_dwordx4 v[218:219], off
	v_lshl_add_u64 v[218:219], v[224:225], 0, s[94:95]
	s_mov_b32 m0, s90
	s_nop 0
	global_load_lds_dwordx4 v[218:219], off
	s_waitcnt vmcnt(8)
	s_waitcnt lgkmcnt(0)
	s_barrier
	v_mfma_f32_16x16x32_bf16 v[62:65], v[130:133], v[162:165], v[62:65]
	v_mfma_f32_16x16x32_bf16 v[58:61], v[138:141], v[162:165], v[58:61]
	v_mfma_f32_16x16x32_bf16 v[54:57], v[130:133], v[170:173], v[54:57]
	v_mfma_f32_16x16x32_bf16 v[50:53], v[138:141], v[170:173], v[50:53]
	v_mfma_f32_16x16x32_bf16 v[38:41], v[130:133], v[178:181], v[38:41]
	v_mfma_f32_16x16x32_bf16 v[34:37], v[138:141], v[178:181], v[34:37]
	v_mfma_f32_16x16x32_bf16 v[22:25], v[130:133], v[186:189], v[22:25]
	v_mfma_f32_16x16x32_bf16 v[18:21], v[138:141], v[186:189], v[18:21]
	v_mfma_f32_16x16x32_bf16 v[62:65], v[134:137], v[166:169], v[62:65]
	v_mfma_f32_16x16x32_bf16 v[58:61], v[142:145], v[166:169], v[58:61]
	v_mfma_f32_16x16x32_bf16 v[54:57], v[134:137], v[174:177], v[54:57]
	v_mfma_f32_16x16x32_bf16 v[50:53], v[142:145], v[174:177], v[50:53]
	v_mfma_f32_16x16x32_bf16 v[38:41], v[134:137], v[182:185], v[38:41]
	v_mfma_f32_16x16x32_bf16 v[34:37], v[142:145], v[182:185], v[34:37]
	v_mfma_f32_16x16x32_bf16 v[22:25], v[134:137], v[190:193], v[22:25]
	v_mfma_f32_16x16x32_bf16 v[18:21], v[142:145], v[190:193], v[18:21]
	v_mfma_f32_16x16x32_bf16 v[46:49], v[146:149], v[162:165], v[46:49]
	v_mfma_f32_16x16x32_bf16 v[42:45], v[154:157], v[162:165], v[42:45]
	v_mfma_f32_16x16x32_bf16 v[30:33], v[146:149], v[170:173], v[30:33]
	v_mfma_f32_16x16x32_bf16 v[26:29], v[154:157], v[170:173], v[26:29]
	v_mfma_f32_16x16x32_bf16 v[14:17], v[146:149], v[178:181], v[14:17]
	v_mfma_f32_16x16x32_bf16 v[10:13], v[154:157], v[178:181], v[10:13]
	v_mfma_f32_16x16x32_bf16 v[6:9], v[146:149], v[186:189], v[6:9]
	v_mfma_f32_16x16x32_bf16 v[2:5], v[154:157], v[186:189], v[2:5]
	v_mfma_f32_16x16x32_bf16 v[46:49], v[150:153], v[166:169], v[46:49]
	v_mfma_f32_16x16x32_bf16 v[42:45], v[158:161], v[166:169], v[42:45]
	v_mfma_f32_16x16x32_bf16 v[30:33], v[150:153], v[174:177], v[30:33]
	v_mfma_f32_16x16x32_bf16 v[26:29], v[158:161], v[174:177], v[26:29]
	v_mfma_f32_16x16x32_bf16 v[14:17], v[150:153], v[182:185], v[14:17]
	v_mfma_f32_16x16x32_bf16 v[10:13], v[158:161], v[182:185], v[10:13]
	v_mfma_f32_16x16x32_bf16 v[6:9], v[150:153], v[190:193], v[6:9]
	v_mfma_f32_16x16x32_bf16 v[2:5], v[158:161], v[190:193], v[2:5]
	s_barrier
	s_add_u32 vcc_hi, vcc_hi, 0x100
	s_addc_u32 s63, s63, 0
	s_add_u32 s30, s30, 0x100
	s_addc_u32 s31, s31, 0
	s_cmp_ge_i32 s56, s1
	s_mov_b32 s34, s56
	s_cbranch_scc0 .LBB0_880
	s_setprio 0
	s_and_b64 vcc, exec, s[12:13]
	s_cbranch_vccz .LBB0_883
	s_barrier

; #define PG8_STAGE(bufoff, gbase, voff) do { _Pragma("unroll") for (int _i = 0; _i < 2; ++_i) \
;         __builtin_amdgcn_global_load_lds((const unsigned*)((const char*)(gbase) + (voff)[_i]), (PG8_LAS unsigned*)(lds + (bufoff) + ldsw + _i * 8192), 16, 0, 0); } while (0)
; #define PG8_LDA(dst, b, h) do { _Pragma("unroll") for (int m = 0; m < 4; ++m) _Pragma("unroll") for (int k = 0; k < 2; ++k) dst[m][k] = *(const PG8_LAS bf16x8*)(lds + PG8_SA(b, h) + aoff + m * 2048 + k * 1024); } while (0)
; #define PG8_LDB(dst, b, h) do { _Pragma("unroll") for (int n = 0; n < 2; ++n) _Pragma("unroll") for (int k = 0; k < 2; ++k) dst[n][k] = *(const PG8_LAS bf16x8*)(lds + PG8_SB(b, h) + boff + n * 2048 + k * 1024); } while (0)
; #define PG8_MMA(ai, bj, At, Bt) do { __builtin_amdgcn_s_setprio(1); _Pragma("unroll") for (int m = 0; m < 4; ++m) _Pragma("unroll") for (int n = 0; n < 2; ++n) _Pragma("unroll") for (int k = 0; k < 2; ++k) \
;         acc[ai][bj][m][n] = __builtin_amdgcn_mfma_f32_16x16x32_bf16(Bt[n][k], At[m][k], acc[ai][bj][m][n], 0, 0, 0); __builtin_amdgcn_s_setprio(0); } while (0)
; #define PG8_WAIT_V(n) asm volatile("s_waitcnt vmcnt(" #n ")" ::: "memory")
; #define PG8_BAR __builtin_amdgcn_s_barrier()
; template <class Epi, class Sched, bool ALIGN_EPI = false, bool SP2 = false>
; __device__ __forceinline__ void gemm_phase(PG8_LAS unsigned char* lds, const Gemm g, const Sched& S, const Epi& E, int wid_in) {
;     ...
;         for (int t = 0; t < nt; t += 2) {
;             const bool last = (t == nt - 2);
;             const char* a1 = cA + (size_t)(t + 1) * kstep;
;             const char* a2 = last ? nA : cA + (size_t)(t + 2) * kstep; const char* b2 = last ? nB : cB + (size_t)(t + 2) * kstep;
;             const char* a3 = a2 + kstep; const char* b3 = b2 + kstep;
;             if (last && has_next) S.a_ready(nxt);
;             if constexpr (SP2) {
;             PG8_LDB(B0, 0, 0); PG8_LDB(B1, 0, 1); PG8_SCHED; PG8_LDA(At, 0, 0); PG8_STAGE(PG8_SA(1, 1), a1 + hstep, voffA);
;             PG8_WAIT_V(8); PG8_WAIT_L(0); PG8_BAR; PG8_MMA(0, 0, At, B0); PG8_MMA(0, 1, At, B1); PG8_BAR; PG8_SCHED;
;             PG8_LDA(At, 0, 1); PG8_STAGE(PG8_SB(0, 0), b2, voffB); PG8_STAGE(PG8_SB(0, 1), b2 + hstep, voffB); PG8_STAGE(PG8_SA(0, 0), a2, voffA);
;             PG8_WAIT_V(8); PG8_WAIT_L(0); PG8_BAR; PG8_MMA(1, 0, At, B0); PG8_MMA(1, 1, At, B1); PG8_BAR; PG8_SCHED;
.Lprio_skip_3:
.LBB0_1021:
	s_add_i32 s56, s27, 2
	s_add_u32 s34, s30, 0xfff80080
	s_addc_u32 s35, s31, -1
	s_add_i32 s40, 0, 0x10000
	s_cmp_eq_u32 s17, s27
	s_cselect_b32 s37, s23, s35
	s_cselect_b32 s36, s22, s34
	s_cselect_b32 s35, s25, s21
	s_cselect_b32 s34, s24, s19
	s_add_i32 s27, 0, 0x14000
	v_add_u32_e32 v142, s40, v176
	v_add_u32_e32 v168, s27, v176
	ds_read_b128 v[130:133], v142
	ds_read_b128 v[134:137], v142 offset:1024
	ds_read_b128 v[138:141], v142 offset:2048
	ds_read_b128 v[142:145], v142 offset:3072
	ds_read_b128 v[146:149], v168
	ds_read_b128 v[160:163], v168 offset:1024
	ds_read_b128 v[164:167], v168 offset:2048
	ds_read_b128 v[168:171], v168 offset:3072
	v_lshl_add_u64 v[220:221], s[30:31], 0, v[158:159]
	s_add_i32 m0, s29, 0xc000
	ds_read_b128 v[172:175], v177
	ds_read_b128 v[178:181], v177 offset:1024
	ds_read_b128 v[182:185], v177 offset:2048
	ds_read_b128 v[186:189], v177 offset:3072
	ds_read_b128 v[190:193], v177 offset:4096
	ds_read_b128 v[208:211], v177 offset:5120
	ds_read_b128 v[212:215], v177 offset:6144
	ds_read_b128 v[216:219], v177 offset:7168
	global_load_lds_dwordx4 v[220:221], off
	v_lshl_add_u64 v[220:221], s[30:31], 0, v[156:157]
	s_add_i32 m0, s29, 0xe000
	s_nop 0
	global_load_lds_dwordx4 v[220:221], off
	s_waitcnt vmcnt(8)
	s_waitcnt lgkmcnt(0)
	s_barrier
	v_mfma_f32_16x16x32_bf16 v[126:129], v[130:133], v[172:175], v[126:129]
	v_mfma_f32_16x16x32_bf16 v[122:125], v[138:141], v[172:175], v[122:125]
	v_mfma_f32_16x16x32_bf16 v[118:121], v[130:133], v[182:185], v[118:121]
	v_mfma_f32_16x16x32_bf16 v[114:117], v[138:141], v[182:185], v[114:117]
	v_mfma_f32_16x16x32_bf16 v[102:105], v[130:133], v[190:193], v[102:105]
	v_mfma_f32_16x16x32_bf16 v[98:101], v[138:141], v[190:193], v[98:101]
	v_mfma_f32_16x16x32_bf16 v[86:89], v[130:133], v[212:215], v[86:89]
	v_mfma_f32_16x16x32_bf16 v[82:85], v[138:141], v[212:215], v[82:85]
	v_mfma_f32_16x16x32_bf16 v[126:129], v[134:137], v[178:181], v[126:129]
	v_mfma_f32_16x16x32_bf16 v[122:125], v[142:145], v[178:181], v[122:125]
	v_mfma_f32_16x16x32_bf16 v[118:121], v[134:137], v[186:189], v[118:121]
	v_mfma_f32_16x16x32_bf16 v[114:117], v[142:145], v[186:189], v[114:117]
	v_mfma_f32_16x16x32_bf16 v[102:105], v[134:137], v[208:211], v[102:105]
	v_mfma_f32_16x16x32_bf16 v[98:101], v[142:145], v[208:211], v[98:101]
	v_mfma_f32_16x16x32_bf16 v[86:89], v[134:137], v[216:219], v[86:89]
	v_mfma_f32_16x16x32_bf16 v[82:85], v[142:145], v[216:219], v[82:85]
	v_mfma_f32_16x16x32_bf16 v[110:113], v[146:149], v[172:175], v[110:113]
	v_mfma_f32_16x16x32_bf16 v[106:109], v[164:167], v[172:175], v[106:109]
	v_mfma_f32_16x16x32_bf16 v[94:97], v[146:149], v[182:185], v[94:97]
	v_mfma_f32_16x16x32_bf16 v[90:93], v[164:167], v[182:185], v[90:93]
	v_mfma_f32_16x16x32_bf16 v[78:81], v[146:149], v[190:193], v[78:81]
	v_mfma_f32_16x16x32_bf16 v[74:77], v[164:167], v[190:193], v[74:77]
	v_mfma_f32_16x16x32_bf16 v[70:73], v[146:149], v[212:215], v[70:73]
	v_mfma_f32_16x16x32_bf16 v[66:69], v[164:167], v[212:215], v[66:69]
	v_mfma_f32_16x16x32_bf16 v[110:113], v[160:163], v[178:181], v[110:113]
	v_mfma_f32_16x16x32_bf16 v[106:109], v[168:171], v[178:181], v[106:109]
	v_mfma_f32_16x16x32_bf16 v[94:97], v[160:163], v[186:189], v[94:97]
	v_mfma_f32_16x16x32_bf16 v[90:93], v[168:171], v[186:189], v[90:93]
	v_mfma_f32_16x16x32_bf16 v[78:81], v[160:163], v[208:211], v[78:81]
	v_mfma_f32_16x16x32_bf16 v[74:77], v[168:171], v[208:211], v[74:77]
	v_mfma_f32_16x16x32_bf16 v[70:73], v[160:163], v[216:219], v[70:73]
	v_mfma_f32_16x16x32_bf16 v[66:69], v[168:171], v[216:219], v[66:69]
	s_barrier
	s_add_i32 s40, s40, s59
	v_lshl_add_u64 v[220:221], s[34:35], 0, v[0:1]
	s_mov_b32 m0, s40
	ds_read_b128 v[172:175], v177 offset:16384
	ds_read_b128 v[178:181], v177 offset:17408
	ds_read_b128 v[182:185], v177 offset:18432
	ds_read_b128 v[186:189], v177 offset:19456
	ds_read_b128 v[190:193], v177 offset:20480
	ds_read_b128 v[208:211], v177 offset:21504
	ds_read_b128 v[212:215], v177 offset:22528
	ds_read_b128 v[216:219], v177 offset:23552
	global_load_lds_dwordx4 v[220:221], off
	s_add_i32 m0, s40, 0x2000
	s_add_u32 s40, s34, 0x80000
	v_lshl_add_u64 v[222:223], s[34:35], 0, v[154:155]
	s_addc_u32 s41, s35, 0
	s_add_i32 s27, s27, s59
	global_load_lds_dwordx4 v[222:223], off
	v_lshl_add_u64 v[224:225], s[40:41], 0, v[0:1]
	s_mov_b32 m0, s27
	v_lshl_add_u64 v[226:227], s[36:37], 0, v[152:153]
	global_load_lds_dwordx4 v[224:225], off
	v_lshl_add_u64 v[224:225], s[40:41], 0, v[154:155]
	s_add_i32 m0, s27, 0x2000
	s_nop 0
	global_load_lds_dwordx4 v[224:225], off
	v_lshl_add_u64 v[224:225], s[36:37], 0, v[150:151]
	s_mov_b32 m0, s29
	s_nop 0
	global_load_lds_dwordx4 v[224:225], off
	s_mov_b32 m0, s52
	s_nop 0
	global_load_lds_dwordx4 v[226:227], off
	s_waitcnt vmcnt(8)
	s_waitcnt lgkmcnt(0)
	s_barrier
; #define PG8_STAGE(bufoff, gbase, voff) do { _Pragma("unroll") for (int _i = 0; _i < 2; ++_i) \
;         __builtin_amdgcn_global_load_lds((const unsigned*)((const char*)(gbase) + (voff)[_i]), (PG8_LAS unsigned*)(lds + (bufoff) + ldsw + _i * 8192), 16, 0, 0); } while (0)
; #define PG8_LDA(dst, b, h) do { _Pragma("unroll") for (int m = 0; m < 4; ++m) _Pragma("unroll") for (int k = 0; k < 2; ++k) dst[m][k] = *(const PG8_LAS bf16x8*)(lds + PG8_SA(b, h) + aoff + m * 2048 + k * 1024); } while (0)
; #define PG8_LDB(dst, b, h) do { _Pragma("unroll") for (int n = 0; n < 2; ++n) _Pragma("unroll") for (int k = 0; k < 2; ++k) dst[n][k] = *(const PG8_LAS bf16x8*)(lds + PG8_SB(b, h) + boff + n * 2048 + k * 1024); } while (0)
; #define PG8_MMA(ai, bj, At, Bt) do { __builtin_amdgcn_s_setprio(1); _Pragma("unroll") for (int m = 0; m < 4; ++m) _Pragma("unroll") for (int n = 0; n < 2; ++n) _Pragma("unroll") for (int k = 0; k < 2; ++k) \
;         acc[ai][bj][m][n] = __builtin_amdgcn_mfma_f32_16x16x32_bf16(Bt[n][k], At[m][k], acc[ai][bj][m][n], 0, 0, 0); __builtin_amdgcn_s_setprio(0); } while (0)
; #define PG8_WAIT_V(n) asm volatile("s_waitcnt vmcnt(" #n ")" ::: "memory")
; #define PG8_WAIT_L(n) asm volatile("s_waitcnt lgkmcnt(" #n ")" ::: "memory")
; #define PG8_BAR __builtin_amdgcn_s_barrier()
; #define PG8_SCHED __builtin_amdgcn_sched_barrier(0)
; template <class Epi, class Sched, bool ALIGN_EPI = false, bool SP2 = false>
; __device__ __forceinline__ void gemm_phase(PG8_LAS unsigned char* lds, const Gemm g, const Sched& S, const Epi& E, int wid_in) {
;     ...
;             PG8_WAIT_V(8); PG8_WAIT_L(0); PG8_BAR; PG8_MMA(1, 0, At, B0); PG8_MMA(1, 1, At, B1); PG8_BAR; PG8_SCHED;
;             PG8_LDB(B0, 1, 0); PG8_LDB(B1, 1, 1); PG8_SCHED; PG8_LDA(At, 1, 0); PG8_STAGE(PG8_SA(0, 1), a2 + hstep, voffA);
;             PG8_WAIT_V(8); PG8_WAIT_L(0); PG8_BAR; PG8_MMA(0, 0, At, B0); PG8_MMA(0, 1, At, B1); PG8_BAR; PG8_SCHED;
	v_mfma_f32_16x16x32_bf16 v[62:65], v[130:133], v[172:175], v[62:65]
	v_mfma_f32_16x16x32_bf16 v[58:61], v[138:141], v[172:175], v[58:61]
	v_mfma_f32_16x16x32_bf16 v[54:57], v[130:133], v[182:185], v[54:57]
	v_mfma_f32_16x16x32_bf16 v[50:53], v[138:141], v[182:185], v[50:53]
	v_mfma_f32_16x16x32_bf16 v[38:41], v[130:133], v[190:193], v[38:41]
	v_mfma_f32_16x16x32_bf16 v[34:37], v[138:141], v[190:193], v[34:37]
	v_mfma_f32_16x16x32_bf16 v[22:25], v[130:133], v[212:215], v[22:25]
	v_mfma_f32_16x16x32_bf16 v[18:21], v[138:141], v[212:215], v[18:21]
	v_mfma_f32_16x16x32_bf16 v[62:65], v[134:137], v[178:181], v[62:65]
	v_mfma_f32_16x16x32_bf16 v[58:61], v[142:145], v[178:181], v[58:61]
	v_mfma_f32_16x16x32_bf16 v[54:57], v[134:137], v[186:189], v[54:57]
	v_mfma_f32_16x16x32_bf16 v[50:53], v[142:145], v[186:189], v[50:53]
	v_mfma_f32_16x16x32_bf16 v[38:41], v[134:137], v[208:211], v[38:41]
	v_mfma_f32_16x16x32_bf16 v[34:37], v[142:145], v[208:211], v[34:37]
	v_mfma_f32_16x16x32_bf16 v[22:25], v[134:137], v[216:219], v[22:25]
	v_mfma_f32_16x16x32_bf16 v[18:21], v[142:145], v[216:219], v[18:21]
	v_mfma_f32_16x16x32_bf16 v[46:49], v[146:149], v[172:175], v[46:49]
	v_mfma_f32_16x16x32_bf16 v[42:45], v[164:167], v[172:175], v[42:45]
	v_mfma_f32_16x16x32_bf16 v[30:33], v[146:149], v[182:185], v[30:33]
	v_mfma_f32_16x16x32_bf16 v[26:29], v[164:167], v[182:185], v[26:29]
	v_mfma_f32_16x16x32_bf16 v[14:17], v[146:149], v[190:193], v[14:17]
	v_mfma_f32_16x16x32_bf16 v[10:13], v[164:167], v[190:193], v[10:13]
	v_mfma_f32_16x16x32_bf16 v[6:9], v[146:149], v[212:215], v[6:9]
	v_mfma_f32_16x16x32_bf16 v[2:5], v[164:167], v[212:215], v[2:5]
	v_mfma_f32_16x16x32_bf16 v[46:49], v[160:163], v[178:181], v[46:49]
	v_mfma_f32_16x16x32_bf16 v[42:45], v[168:171], v[178:181], v[42:45]
	v_mfma_f32_16x16x32_bf16 v[30:33], v[160:163], v[186:189], v[30:33]
	v_mfma_f32_16x16x32_bf16 v[26:29], v[168:171], v[186:189], v[26:29]
	v_mfma_f32_16x16x32_bf16 v[14:17], v[160:163], v[208:211], v[14:17]
	v_mfma_f32_16x16x32_bf16 v[10:13], v[168:171], v[208:211], v[10:13]
	v_mfma_f32_16x16x32_bf16 v[6:9], v[160:163], v[216:219], v[6:9]
	v_mfma_f32_16x16x32_bf16 v[2:5], v[168:171], v[216:219], v[2:5]
	s_barrier
	s_add_i32 s27, 0, 0x18000
	s_add_i32 s40, 0, 0x1c000
	v_add_u32_e32 v142, s27, v176
	v_add_u32_e32 v168, s40, v176
	ds_read_b128 v[130:133], v142
	ds_read_b128 v[134:137], v142 offset:1024
	ds_read_b128 v[138:141], v142 offset:2048
	ds_read_b128 v[142:145], v142 offset:3072
	ds_read_b128 v[146:149], v168
	ds_read_b128 v[160:163], v168 offset:1024
	ds_read_b128 v[164:167], v168 offset:2048
	ds_read_b128 v[168:171], v168 offset:3072
	s_add_u32 s36, s36, 0x80000
	s_addc_u32 s37, s37, 0
	s_mov_b32 m0, s53
	v_lshl_add_u64 v[228:229], s[36:37], 0, v[150:151]
	ds_read_b128 v[172:175], v177 offset:32768
	ds_read_b128 v[178:181], v177 offset:33792
	ds_read_b128 v[182:185], v177 offset:34816
	ds_read_b128 v[186:189], v177 offset:35840
	ds_read_b128 v[190:193], v177 offset:36864
	ds_read_b128 v[208:211], v177 offset:37888
	ds_read_b128 v[212:215], v177 offset:38912
	ds_read_b128 v[216:219], v177 offset:39936
	global_load_lds_dwordx4 v[228:229], off
	v_lshl_add_u64 v[228:229], s[36:37], 0, v[152:153]
	s_mov_b32 m0, s61
	s_nop 0
	global_load_lds_dwordx4 v[228:229], off
	s_waitcnt vmcnt(8)
	s_waitcnt lgkmcnt(0)
	s_barrier
	v_mfma_f32_16x16x32_bf16 v[126:129], v[130:133], v[172:175], v[126:129]
	v_mfma_f32_16x16x32_bf16 v[122:125], v[138:141], v[172:175], v[122:125]
	v_mfma_f32_16x16x32_bf16 v[118:121], v[130:133], v[182:185], v[118:121]
	v_mfma_f32_16x16x32_bf16 v[114:117], v[138:141], v[182:185], v[114:117]
	v_mfma_f32_16x16x32_bf16 v[102:105], v[130:133], v[190:193], v[102:105]
	v_mfma_f32_16x16x32_bf16 v[98:101], v[138:141], v[190:193], v[98:101]
	v_mfma_f32_16x16x32_bf16 v[86:89], v[130:133], v[212:215], v[86:89]
	v_mfma_f32_16x16x32_bf16 v[82:85], v[138:141], v[212:215], v[82:85]
	v_mfma_f32_16x16x32_bf16 v[126:129], v[134:137], v[178:181], v[126:129]
	v_mfma_f32_16x16x32_bf16 v[122:125], v[142:145], v[178:181], v[122:125]
	v_mfma_f32_16x16x32_bf16 v[118:121], v[134:137], v[186:189], v[118:121]
	v_mfma_f32_16x16x32_bf16 v[114:117], v[142:145], v[186:189], v[114:117]
	v_mfma_f32_16x16x32_bf16 v[102:105], v[134:137], v[208:211], v[102:105]
	v_mfma_f32_16x16x32_bf16 v[98:101], v[142:145], v[208:211], v[98:101]
	v_mfma_f32_16x16x32_bf16 v[86:89], v[134:137], v[216:219], v[86:89]
	v_mfma_f32_16x16x32_bf16 v[82:85], v[142:145], v[216:219], v[82:85]
	v_mfma_f32_16x16x32_bf16 v[110:113], v[146:149], v[172:175], v[110:113]
	v_mfma_f32_16x16x32_bf16 v[106:109], v[164:167], v[172:175], v[106:109]
	v_mfma_f32_16x16x32_bf16 v[94:97], v[146:149], v[182:185], v[94:97]
	v_mfma_f32_16x16x32_bf16 v[90:93], v[164:167], v[182:185], v[90:93]
	v_mfma_f32_16x16x32_bf16 v[78:81], v[146:149], v[190:193], v[78:81]
	v_mfma_f32_16x16x32_bf16 v[74:77], v[164:167], v[190:193], v[74:77]
	v_mfma_f32_16x16x32_bf16 v[70:73], v[146:149], v[212:215], v[70:73]
	v_mfma_f32_16x16x32_bf16 v[66:69], v[164:167], v[212:215], v[66:69]
	v_mfma_f32_16x16x32_bf16 v[110:113], v[160:163], v[178:181], v[110:113]
	v_mfma_f32_16x16x32_bf16 v[106:109], v[168:171], v[178:181], v[106:109]
	v_mfma_f32_16x16x32_bf16 v[94:97], v[160:163], v[186:189], v[94:97]
	v_mfma_f32_16x16x32_bf16 v[90:93], v[168:171], v[186:189], v[90:93]
	v_mfma_f32_16x16x32_bf16 v[78:81], v[160:163], v[208:211], v[78:81]
	v_mfma_f32_16x16x32_bf16 v[74:77], v[168:171], v[208:211], v[74:77]
	v_mfma_f32_16x16x32_bf16 v[70:73], v[160:163], v[216:219], v[70:73]
	v_mfma_f32_16x16x32_bf16 v[66:69], v[168:171], v[216:219], v[66:69]
	s_barrier
; #define PG8_STAGE(bufoff, gbase, voff) do { _Pragma("unroll") for (int _i = 0; _i < 2; ++_i) \
;         __builtin_amdgcn_global_load_lds((const unsigned*)((const char*)(gbase) + (voff)[_i]), (PG8_LAS unsigned*)(lds + (bufoff) + ldsw + _i * 8192), 16, 0, 0); } while (0)
; #define PG8_LDA(dst, b, h) do { _Pragma("unroll") for (int m = 0; m < 4; ++m) _Pragma("unroll") for (int k = 0; k < 2; ++k) dst[m][k] = *(const PG8_LAS bf16x8*)(lds + PG8_SA(b, h) + aoff + m * 2048 + k * 1024); } while (0)
; #define PG8_MMA(ai, bj, At, Bt) do { __builtin_amdgcn_s_setprio(1); _Pragma("unroll") for (int m = 0; m < 4; ++m) _Pragma("unroll") for (int n = 0; n < 2; ++n) _Pragma("unroll") for (int k = 0; k < 2; ++k) \
;         acc[ai][bj][m][n] = __builtin_amdgcn_mfma_f32_16x16x32_bf16(Bt[n][k], At[m][k], acc[ai][bj][m][n], 0, 0, 0); __builtin_amdgcn_s_setprio(0); } while (0)
; #define PG8_WAIT_V(n) asm volatile("s_waitcnt vmcnt(" #n ")" ::: "memory")
; #define PG8_WAIT_L(n) asm volatile("s_waitcnt lgkmcnt(" #n ")" ::: "memory")
; #define PG8_BAR __builtin_amdgcn_s_barrier()
; #define PG8_SCHED __builtin_amdgcn_sched_barrier(0)
; template <class Epi, class Sched, bool ALIGN_EPI = false, bool SP2 = false>
; __device__ __forceinline__ void gemm_phase(PG8_LAS unsigned char* lds, const Gemm g, const Sched& S, const Epi& E, int wid_in) {
;     ...
;             PG8_LDA(At, 1, 1); PG8_STAGE(PG8_SB(1, 0), b3, voffB); PG8_STAGE(PG8_SB(1, 1), b3 + hstep, voffB); PG8_STAGE(PG8_SA(1, 0), a3, voffA);
;             PG8_WAIT_V(8); PG8_WAIT_L(0); PG8_BAR; PG8_MMA(1, 0, At, B0); PG8_MMA(1, 1, At, B1); PG8_BAR; PG8_SCHED;
;     ...
;         if constexpr (ALIGN_EPI) { if (wr == 0) PG8_BAR; }
	s_add_i32 s27, s27, s59
	v_lshl_add_u64 v[220:221], v[220:221], 0, s[94:95]
	s_mov_b32 m0, s27
	ds_read_b128 v[172:175], v177 offset:49152
	ds_read_b128 v[178:181], v177 offset:50176
	ds_read_b128 v[182:185], v177 offset:51200
	ds_read_b128 v[186:189], v177 offset:52224
	ds_read_b128 v[190:193], v177 offset:53248
	ds_read_b128 v[208:211], v177 offset:54272
	ds_read_b128 v[212:215], v177 offset:55296
	ds_read_b128 v[216:219], v177 offset:56320
	global_load_lds_dwordx4 v[220:221], off
	s_add_i32 m0, s27, 0x2000
	s_add_u32 s34, s34, 0x80080
	v_lshl_add_u64 v[220:221], v[222:223], 0, s[94:95]
	s_addc_u32 s35, s35, 0
	s_add_i32 s27, s40, s59
	global_load_lds_dwordx4 v[220:221], off
	v_lshl_add_u64 v[220:221], s[34:35], 0, v[0:1]
	s_mov_b32 m0, s27
	s_nop 0
	global_load_lds_dwordx4 v[220:221], off
	v_lshl_add_u64 v[220:221], s[34:35], 0, v[154:155]
	s_add_i32 m0, s27, 0x2000
	s_nop 0
	global_load_lds_dwordx4 v[220:221], off
	v_lshl_add_u64 v[220:221], v[224:225], 0, s[94:95]
	s_mov_b32 m0, s73
	s_nop 0
	global_load_lds_dwordx4 v[220:221], off
	v_lshl_add_u64 v[220:221], v[226:227], 0, s[94:95]
	s_mov_b32 m0, s80
	s_nop 0
	global_load_lds_dwordx4 v[220:221], off
	s_waitcnt vmcnt(8)
	s_waitcnt lgkmcnt(0)
	s_barrier
	v_mfma_f32_16x16x32_bf16 v[62:65], v[130:133], v[172:175], v[62:65]
	v_mfma_f32_16x16x32_bf16 v[58:61], v[138:141], v[172:175], v[58:61]
	v_mfma_f32_16x16x32_bf16 v[54:57], v[130:133], v[182:185], v[54:57]
	v_mfma_f32_16x16x32_bf16 v[50:53], v[138:141], v[182:185], v[50:53]
	v_mfma_f32_16x16x32_bf16 v[38:41], v[130:133], v[190:193], v[38:41]
	v_mfma_f32_16x16x32_bf16 v[34:37], v[138:141], v[190:193], v[34:37]
	v_mfma_f32_16x16x32_bf16 v[22:25], v[130:133], v[212:215], v[22:25]
	v_mfma_f32_16x16x32_bf16 v[18:21], v[138:141], v[212:215], v[18:21]
	v_mfma_f32_16x16x32_bf16 v[62:65], v[134:137], v[178:181], v[62:65]
	v_mfma_f32_16x16x32_bf16 v[58:61], v[142:145], v[178:181], v[58:61]
	v_mfma_f32_16x16x32_bf16 v[54:57], v[134:137], v[186:189], v[54:57]
	v_mfma_f32_16x16x32_bf16 v[50:53], v[142:145], v[186:189], v[50:53]
	v_mfma_f32_16x16x32_bf16 v[38:41], v[134:137], v[208:211], v[38:41]
	v_mfma_f32_16x16x32_bf16 v[34:37], v[142:145], v[208:211], v[34:37]
	v_mfma_f32_16x16x32_bf16 v[22:25], v[134:137], v[216:219], v[22:25]
	v_mfma_f32_16x16x32_bf16 v[18:21], v[142:145], v[216:219], v[18:21]
	v_mfma_f32_16x16x32_bf16 v[46:49], v[146:149], v[172:175], v[46:49]
	v_mfma_f32_16x16x32_bf16 v[42:45], v[164:167], v[172:175], v[42:45]
	v_mfma_f32_16x16x32_bf16 v[30:33], v[146:149], v[182:185], v[30:33]
	v_mfma_f32_16x16x32_bf16 v[26:29], v[164:167], v[182:185], v[26:29]
	v_mfma_f32_16x16x32_bf16 v[14:17], v[146:149], v[190:193], v[14:17]
	v_mfma_f32_16x16x32_bf16 v[10:13], v[164:167], v[190:193], v[10:13]
	v_mfma_f32_16x16x32_bf16 v[6:9], v[146:149], v[212:215], v[6:9]
	v_mfma_f32_16x16x32_bf16 v[2:5], v[164:167], v[212:215], v[2:5]
	v_mfma_f32_16x16x32_bf16 v[46:49], v[160:163], v[178:181], v[46:49]
	v_mfma_f32_16x16x32_bf16 v[42:45], v[168:171], v[178:181], v[42:45]
	v_mfma_f32_16x16x32_bf16 v[30:33], v[160:163], v[186:189], v[30:33]
	v_mfma_f32_16x16x32_bf16 v[26:29], v[168:171], v[186:189], v[26:29]
	v_mfma_f32_16x16x32_bf16 v[14:17], v[160:163], v[208:211], v[14:17]
	v_mfma_f32_16x16x32_bf16 v[10:13], v[168:171], v[208:211], v[10:13]
	v_mfma_f32_16x16x32_bf16 v[6:9], v[160:163], v[216:219], v[6:9]
	v_mfma_f32_16x16x32_bf16 v[2:5], v[168:171], v[216:219], v[2:5]
	s_barrier
	s_add_u32 s19, s19, 0x100
	s_addc_u32 s21, s21, 0
	s_add_u32 s30, s30, 0x100
	s_addc_u32 s31, s31, 0
	s_cmp_ge_i32 s56, s90
	s_mov_b32 s27, s56
	s_cbranch_scc0 .LBB0_1021
	s_setprio 0
	s_and_b64 vcc, exec, s[14:15]
	s_cbranch_vccz .LBB0_1024
	s_barrier

; #define PG8_STAGE(bufoff, gbase, voff) do { _Pragma("unroll") for (int _i = 0; _i < 2; ++_i) \
;         __builtin_amdgcn_global_load_lds((const unsigned*)((const char*)(gbase) + (voff)[_i]), (PG8_LAS unsigned*)(lds + (bufoff) + ldsw + _i * 8192), 16, 0, 0); } while (0)
; #define PG8_LDA(dst, b, h) do { _Pragma("unroll") for (int m = 0; m < 4; ++m) _Pragma("unroll") for (int k = 0; k < 2; ++k) dst[m][k] = *(const PG8_LAS bf16x8*)(lds + PG8_SA(b, h) + aoff + m * 2048 + k * 1024); } while (0)
; #define PG8_LDB(dst, b, h) do { _Pragma("unroll") for (int n = 0; n < 2; ++n) _Pragma("unroll") for (int k = 0; k < 2; ++k) dst[n][k] = *(const PG8_LAS bf16x8*)(lds + PG8_SB(b, h) + boff + n * 2048 + k * 1024); } while (0)
; #define PG8_MMA(ai, bj, At, Bt) do { __builtin_amdgcn_s_setprio(1); _Pragma("unroll") for (int m = 0; m < 4; ++m) _Pragma("unroll") for (int n = 0; n < 2; ++n) _Pragma("unroll") for (int k = 0; k < 2; ++k) \
;         acc[ai][bj][m][n] = __builtin_amdgcn_mfma_f32_16x16x32_bf16(Bt[n][k], At[m][k], acc[ai][bj][m][n], 0, 0, 0); __builtin_amdgcn_s_setprio(0); } while (0)
; #define PG8_WAIT_V(n) asm volatile("s_waitcnt vmcnt(" #n ")" ::: "memory")
; #define PG8_BAR __builtin_amdgcn_s_barrier()
; template <class Epi, class Sched, bool ALIGN_EPI = false, bool SP2 = false>
; __device__ __forceinline__ void gemm_phase(PG8_LAS unsigned char* lds, const Gemm g, const Sched& S, const Epi& E, int wid_in) {
;     ...
;         for (int t = 0; t < nt; t += 2) {
;             const bool last = (t == nt - 2);
;             const char* a1 = cA + (size_t)(t + 1) * kstep;
;             const char* a2 = last ? nA : cA + (size_t)(t + 2) * kstep; const char* b2 = last ? nB : cB + (size_t)(t + 2) * kstep;
;             const char* a3 = a2 + kstep; const char* b3 = b2 + kstep;
;             if (last && has_next) S.a_ready(nxt);
;             if constexpr (SP2) {
;             PG8_LDB(B0, 0, 0); PG8_LDB(B1, 0, 1); PG8_SCHED; PG8_LDA(At, 0, 0); PG8_STAGE(PG8_SA(1, 1), a1 + hstep, voffA);
;             PG8_WAIT_V(8); PG8_WAIT_L(0); PG8_BAR; PG8_MMA(0, 0, At, B0); PG8_MMA(0, 1, At, B1); PG8_BAR; PG8_SCHED;
;             PG8_LDA(At, 0, 1); PG8_STAGE(PG8_SB(0, 0), b2, voffB); PG8_STAGE(PG8_SB(0, 1), b2 + hstep, voffB); PG8_STAGE(PG8_SA(0, 0), a2, voffA);
;             PG8_WAIT_V(8); PG8_WAIT_L(0); PG8_BAR; PG8_MMA(1, 0, At, B0); PG8_MMA(1, 1, At, B1); PG8_BAR; PG8_SCHED;
.Lprio_skip_4:
.LBB0_1153:
	s_add_u32 s26, s24, 0xfff80080
	s_addc_u32 s27, s25, -1
	s_add_i32 s40, 0, 0x10000
	s_cmp_eq_u32 s73, 28
	s_cselect_b32 s29, s19, s27
	s_cselect_b32 s28, s64, s26
	v_add_u32_e32 v140, s40, v142
	s_cselect_b32 s27, s17, s63
	s_cselect_b32 s26, s65, s72
	s_add_i32 s42, 0, 0x14000
	ds_read_b128 v[144:147], v140
	ds_read_b128 v[148:151], v140 offset:1024
	ds_read_b128 v[152:155], v140 offset:2048
	ds_read_b128 v[156:159], v140 offset:3072
	v_add_u32_e32 v140, s42, v142
	ds_read_b128 v[160:163], v140
	ds_read_b128 v[164:167], v140 offset:1024
	ds_read_b128 v[168:171], v140 offset:2048
	ds_read_b128 v[172:175], v140 offset:3072
	v_lshl_add_u64 v[140:141], s[24:25], 0, v[138:139]
	s_add_i32 m0, s34, 0xc000
	ds_read_b128 v[176:179], v143
	ds_read_b128 v[180:183], v143 offset:1024
	ds_read_b128 v[184:187], v143 offset:2048
	ds_read_b128 v[188:191], v143 offset:3072
	ds_read_b128 v[208:211], v143 offset:4096
	ds_read_b128 v[212:215], v143 offset:5120
	ds_read_b128 v[216:219], v143 offset:6144
	ds_read_b128 v[220:223], v143 offset:7168
	global_load_lds_dwordx4 v[140:141], off
	v_lshl_add_u64 v[140:141], s[24:25], 0, v[136:137]
	s_add_i32 m0, s34, 0xe000
	s_nop 0
	global_load_lds_dwordx4 v[140:141], off
	s_waitcnt vmcnt(8)
	s_waitcnt lgkmcnt(0)
	s_barrier
	v_mfma_f32_16x16x32_bf16 v[126:129], v[144:147], v[176:179], v[126:129]
	v_mfma_f32_16x16x32_bf16 v[122:125], v[152:155], v[176:179], v[122:125]
	v_mfma_f32_16x16x32_bf16 v[110:113], v[144:147], v[184:187], v[110:113]
	v_mfma_f32_16x16x32_bf16 v[106:109], v[152:155], v[184:187], v[106:109]
	v_mfma_f32_16x16x32_bf16 v[94:97], v[144:147], v[208:211], v[94:97]
	v_mfma_f32_16x16x32_bf16 v[90:93], v[152:155], v[208:211], v[90:93]
	v_mfma_f32_16x16x32_bf16 v[78:81], v[144:147], v[216:219], v[78:81]
	v_mfma_f32_16x16x32_bf16 v[74:77], v[152:155], v[216:219], v[74:77]
	v_mfma_f32_16x16x32_bf16 v[126:129], v[148:151], v[180:183], v[126:129]
	v_mfma_f32_16x16x32_bf16 v[122:125], v[156:159], v[180:183], v[122:125]
	v_mfma_f32_16x16x32_bf16 v[110:113], v[148:151], v[188:191], v[110:113]
	v_mfma_f32_16x16x32_bf16 v[106:109], v[156:159], v[188:191], v[106:109]
	v_mfma_f32_16x16x32_bf16 v[94:97], v[148:151], v[212:215], v[94:97]
	v_mfma_f32_16x16x32_bf16 v[90:93], v[156:159], v[212:215], v[90:93]
	v_mfma_f32_16x16x32_bf16 v[78:81], v[148:151], v[220:223], v[78:81]
	v_mfma_f32_16x16x32_bf16 v[74:77], v[156:159], v[220:223], v[74:77]
	v_mfma_f32_16x16x32_bf16 v[118:121], v[160:163], v[176:179], v[118:121]
	v_mfma_f32_16x16x32_bf16 v[114:117], v[168:171], v[176:179], v[114:117]
	v_mfma_f32_16x16x32_bf16 v[102:105], v[160:163], v[184:187], v[102:105]
	v_mfma_f32_16x16x32_bf16 v[98:101], v[168:171], v[184:187], v[98:101]
	v_mfma_f32_16x16x32_bf16 v[86:89], v[160:163], v[208:211], v[86:89]
	v_mfma_f32_16x16x32_bf16 v[82:85], v[168:171], v[208:211], v[82:85]
	v_mfma_f32_16x16x32_bf16 v[70:73], v[160:163], v[216:219], v[70:73]
	v_mfma_f32_16x16x32_bf16 v[66:69], v[168:171], v[216:219], v[66:69]
	v_mfma_f32_16x16x32_bf16 v[118:121], v[164:167], v[180:183], v[118:121]
	v_mfma_f32_16x16x32_bf16 v[114:117], v[172:175], v[180:183], v[114:117]
	v_mfma_f32_16x16x32_bf16 v[102:105], v[164:167], v[188:191], v[102:105]
	v_mfma_f32_16x16x32_bf16 v[98:101], v[172:175], v[188:191], v[98:101]
	v_mfma_f32_16x16x32_bf16 v[86:89], v[164:167], v[212:215], v[86:89]
	v_mfma_f32_16x16x32_bf16 v[82:85], v[172:175], v[212:215], v[82:85]
	v_mfma_f32_16x16x32_bf16 v[70:73], v[164:167], v[220:223], v[70:73]
	v_mfma_f32_16x16x32_bf16 v[66:69], v[172:175], v[220:223], v[66:69]
	s_barrier
	s_add_i32 s40, s40, s59
	v_lshl_add_u64 v[140:141], s[26:27], 0, v[0:1]
	s_mov_b32 m0, s40
	ds_read_b128 v[176:179], v143 offset:16384
	ds_read_b128 v[180:183], v143 offset:17408
	ds_read_b128 v[184:187], v143 offset:18432
	ds_read_b128 v[188:191], v143 offset:19456
	ds_read_b128 v[208:211], v143 offset:20480
	ds_read_b128 v[212:215], v143 offset:21504
	ds_read_b128 v[216:219], v143 offset:22528
	ds_read_b128 v[220:223], v143 offset:23552
	global_load_lds_dwordx4 v[140:141], off
	s_add_i32 m0, s40, 0x2000
	s_add_u32 s40, s26, 0x80000
	v_lshl_add_u64 v[192:193], s[26:27], 0, v[130:131]
	s_addc_u32 s41, s27, 0
	s_add_i32 s42, s42, s59
	global_load_lds_dwordx4 v[192:193], off
	v_lshl_add_u64 v[224:225], s[40:41], 0, v[0:1]
	s_mov_b32 m0, s42
	v_lshl_add_u64 v[226:227], s[28:29], 0, v[132:133]
	global_load_lds_dwordx4 v[224:225], off
	v_lshl_add_u64 v[224:225], s[40:41], 0, v[130:131]
	s_add_i32 m0, s42, 0x2000
	s_nop 0
	global_load_lds_dwordx4 v[224:225], off
	v_lshl_add_u64 v[224:225], s[28:29], 0, v[134:135]
	s_mov_b32 m0, s34
	s_nop 0
	global_load_lds_dwordx4 v[224:225], off
	s_mov_b32 m0, s35
	s_nop 0
	global_load_lds_dwordx4 v[226:227], off
	s_waitcnt vmcnt(8)
	s_waitcnt lgkmcnt(0)
	s_barrier
; #define PG8_STAGE(bufoff, gbase, voff) do { _Pragma("unroll") for (int _i = 0; _i < 2; ++_i) \
;         __builtin_amdgcn_global_load_lds((const unsigned*)((const char*)(gbase) + (voff)[_i]), (PG8_LAS unsigned*)(lds + (bufoff) + ldsw + _i * 8192), 16, 0, 0); } while (0)
; #define PG8_LDA(dst, b, h) do { _Pragma("unroll") for (int m = 0; m < 4; ++m) _Pragma("unroll") for (int k = 0; k < 2; ++k) dst[m][k] = *(const PG8_LAS bf16x8*)(lds + PG8_SA(b, h) + aoff + m * 2048 + k * 1024); } while (0)
; #define PG8_LDB(dst, b, h) do { _Pragma("unroll") for (int n = 0; n < 2; ++n) _Pragma("unroll") for (int k = 0; k < 2; ++k) dst[n][k] = *(const PG8_LAS bf16x8*)(lds + PG8_SB(b, h) + boff + n * 2048 + k * 1024); } while (0)
; #define PG8_MMA(ai, bj, At, Bt) do { __builtin_amdgcn_s_setprio(1); _Pragma("unroll") for (int m = 0; m < 4; ++m) _Pragma("unroll") for (int n = 0; n < 2; ++n) _Pragma("unroll") for (int k = 0; k < 2; ++k) \
;         acc[ai][bj][m][n] = __builtin_amdgcn_mfma_f32_16x16x32_bf16(Bt[n][k], At[m][k], acc[ai][bj][m][n], 0, 0, 0); __builtin_amdgcn_s_setprio(0); } while (0)
; #define PG8_WAIT_V(n) asm volatile("s_waitcnt vmcnt(" #n ")" ::: "memory")
; #define PG8_WAIT_L(n) asm volatile("s_waitcnt lgkmcnt(" #n ")" ::: "memory")
; #define PG8_BAR __builtin_amdgcn_s_barrier()
; #define PG8_SCHED __builtin_amdgcn_sched_barrier(0)
; template <class Epi, class Sched, bool ALIGN_EPI = false, bool SP2 = false>
; __device__ __forceinline__ void gemm_phase(PG8_LAS unsigned char* lds, const Gemm g, const Sched& S, const Epi& E, int wid_in) {
;     ...
;             PG8_WAIT_V(8); PG8_WAIT_L(0); PG8_BAR; PG8_MMA(1, 0, At, B0); PG8_MMA(1, 1, At, B1); PG8_BAR; PG8_SCHED;
;             PG8_LDB(B0, 1, 0); PG8_LDB(B1, 1, 1); PG8_SCHED; PG8_LDA(At, 1, 0); PG8_STAGE(PG8_SA(0, 1), a2 + hstep, voffA);
;             PG8_WAIT_V(8); PG8_WAIT_L(0); PG8_BAR; PG8_MMA(0, 0, At, B0); PG8_MMA(0, 1, At, B1); PG8_BAR; PG8_SCHED;
	v_mfma_f32_16x16x32_bf16 v[62:65], v[144:147], v[176:179], v[62:65]
	v_mfma_f32_16x16x32_bf16 v[58:61], v[152:155], v[176:179], v[58:61]
	v_mfma_f32_16x16x32_bf16 v[46:49], v[144:147], v[184:187], v[46:49]
	v_mfma_f32_16x16x32_bf16 v[42:45], v[152:155], v[184:187], v[42:45]
	v_mfma_f32_16x16x32_bf16 v[30:33], v[144:147], v[208:211], v[30:33]
	v_mfma_f32_16x16x32_bf16 v[26:29], v[152:155], v[208:211], v[26:29]
	v_mfma_f32_16x16x32_bf16 v[14:17], v[144:147], v[216:219], v[14:17]
	v_mfma_f32_16x16x32_bf16 v[10:13], v[152:155], v[216:219], v[10:13]
	v_mfma_f32_16x16x32_bf16 v[62:65], v[148:151], v[180:183], v[62:65]
	v_mfma_f32_16x16x32_bf16 v[58:61], v[156:159], v[180:183], v[58:61]
	v_mfma_f32_16x16x32_bf16 v[46:49], v[148:151], v[188:191], v[46:49]
	v_mfma_f32_16x16x32_bf16 v[42:45], v[156:159], v[188:191], v[42:45]
	v_mfma_f32_16x16x32_bf16 v[30:33], v[148:151], v[212:215], v[30:33]
	v_mfma_f32_16x16x32_bf16 v[26:29], v[156:159], v[212:215], v[26:29]
	v_mfma_f32_16x16x32_bf16 v[14:17], v[148:151], v[220:223], v[14:17]
	v_mfma_f32_16x16x32_bf16 v[10:13], v[156:159], v[220:223], v[10:13]
	v_mfma_f32_16x16x32_bf16 v[54:57], v[160:163], v[176:179], v[54:57]
	v_mfma_f32_16x16x32_bf16 v[50:53], v[168:171], v[176:179], v[50:53]
	v_mfma_f32_16x16x32_bf16 v[38:41], v[160:163], v[184:187], v[38:41]
	v_mfma_f32_16x16x32_bf16 v[34:37], v[168:171], v[184:187], v[34:37]
	v_mfma_f32_16x16x32_bf16 v[22:25], v[160:163], v[208:211], v[22:25]
	v_mfma_f32_16x16x32_bf16 v[18:21], v[168:171], v[208:211], v[18:21]
	v_mfma_f32_16x16x32_bf16 v[6:9], v[160:163], v[216:219], v[6:9]
	v_mfma_f32_16x16x32_bf16 v[2:5], v[168:171], v[216:219], v[2:5]
	v_mfma_f32_16x16x32_bf16 v[54:57], v[164:167], v[180:183], v[54:57]
	v_mfma_f32_16x16x32_bf16 v[50:53], v[172:175], v[180:183], v[50:53]
	v_mfma_f32_16x16x32_bf16 v[38:41], v[164:167], v[188:191], v[38:41]
	v_mfma_f32_16x16x32_bf16 v[34:37], v[172:175], v[188:191], v[34:37]
	v_mfma_f32_16x16x32_bf16 v[22:25], v[164:167], v[212:215], v[22:25]
	v_mfma_f32_16x16x32_bf16 v[18:21], v[172:175], v[212:215], v[18:21]
	v_mfma_f32_16x16x32_bf16 v[6:9], v[164:167], v[220:223], v[6:9]
	v_mfma_f32_16x16x32_bf16 v[2:5], v[172:175], v[220:223], v[2:5]
	s_barrier
	s_add_i32 s40, 0, 0x18000
	s_add_i32 s41, 0, 0x1c000
	v_add_u32_e32 v156, s40, v142
	v_add_u32_e32 v172, s41, v142
	ds_read_b128 v[144:147], v156
	ds_read_b128 v[148:151], v156 offset:1024
	ds_read_b128 v[152:155], v156 offset:2048
	ds_read_b128 v[156:159], v156 offset:3072
	ds_read_b128 v[160:163], v172
	ds_read_b128 v[164:167], v172 offset:1024
	ds_read_b128 v[168:171], v172 offset:2048
	ds_read_b128 v[172:175], v172 offset:3072
	s_add_u32 s28, s28, 0x80000
	s_addc_u32 s29, s29, 0
	s_mov_b32 m0, s36
	v_lshl_add_u64 v[228:229], s[28:29], 0, v[134:135]
	ds_read_b128 v[176:179], v143 offset:32768
	ds_read_b128 v[180:183], v143 offset:33792
	ds_read_b128 v[184:187], v143 offset:34816
	ds_read_b128 v[188:191], v143 offset:35840
	ds_read_b128 v[208:211], v143 offset:36864
	ds_read_b128 v[212:215], v143 offset:37888
	ds_read_b128 v[216:219], v143 offset:38912
	ds_read_b128 v[220:223], v143 offset:39936
	global_load_lds_dwordx4 v[228:229], off
	v_lshl_add_u64 v[228:229], s[28:29], 0, v[132:133]
	s_mov_b32 m0, s37
	s_nop 0
	global_load_lds_dwordx4 v[228:229], off
	s_waitcnt vmcnt(8)
	s_waitcnt lgkmcnt(0)
	s_barrier
	v_mfma_f32_16x16x32_bf16 v[126:129], v[144:147], v[176:179], v[126:129]
	v_mfma_f32_16x16x32_bf16 v[122:125], v[152:155], v[176:179], v[122:125]
	v_mfma_f32_16x16x32_bf16 v[110:113], v[144:147], v[184:187], v[110:113]
	v_mfma_f32_16x16x32_bf16 v[106:109], v[152:155], v[184:187], v[106:109]
	v_mfma_f32_16x16x32_bf16 v[94:97], v[144:147], v[208:211], v[94:97]
	v_mfma_f32_16x16x32_bf16 v[90:93], v[152:155], v[208:211], v[90:93]
	v_mfma_f32_16x16x32_bf16 v[78:81], v[144:147], v[216:219], v[78:81]
	v_mfma_f32_16x16x32_bf16 v[74:77], v[152:155], v[216:219], v[74:77]
	v_mfma_f32_16x16x32_bf16 v[126:129], v[148:151], v[180:183], v[126:129]
	v_mfma_f32_16x16x32_bf16 v[122:125], v[156:159], v[180:183], v[122:125]
	v_mfma_f32_16x16x32_bf16 v[110:113], v[148:151], v[188:191], v[110:113]
	v_mfma_f32_16x16x32_bf16 v[106:109], v[156:159], v[188:191], v[106:109]
	v_mfma_f32_16x16x32_bf16 v[94:97], v[148:151], v[212:215], v[94:97]
	v_mfma_f32_16x16x32_bf16 v[90:93], v[156:159], v[212:215], v[90:93]
	v_mfma_f32_16x16x32_bf16 v[78:81], v[148:151], v[220:223], v[78:81]
	v_mfma_f32_16x16x32_bf16 v[74:77], v[156:159], v[220:223], v[74:77]
	v_mfma_f32_16x16x32_bf16 v[118:121], v[160:163], v[176:179], v[118:121]
	v_mfma_f32_16x16x32_bf16 v[114:117], v[168:171], v[176:179], v[114:117]
	v_mfma_f32_16x16x32_bf16 v[102:105], v[160:163], v[184:187], v[102:105]
	v_mfma_f32_16x16x32_bf16 v[98:101], v[168:171], v[184:187], v[98:101]
	v_mfma_f32_16x16x32_bf16 v[86:89], v[160:163], v[208:211], v[86:89]
	v_mfma_f32_16x16x32_bf16 v[82:85], v[168:171], v[208:211], v[82:85]
	v_mfma_f32_16x16x32_bf16 v[70:73], v[160:163], v[216:219], v[70:73]
	v_mfma_f32_16x16x32_bf16 v[66:69], v[168:171], v[216:219], v[66:69]
	v_mfma_f32_16x16x32_bf16 v[118:121], v[164:167], v[180:183], v[118:121]
	v_mfma_f32_16x16x32_bf16 v[114:117], v[172:175], v[180:183], v[114:117]
	v_mfma_f32_16x16x32_bf16 v[102:105], v[164:167], v[188:191], v[102:105]
	v_mfma_f32_16x16x32_bf16 v[98:101], v[172:175], v[188:191], v[98:101]
	v_mfma_f32_16x16x32_bf16 v[86:89], v[164:167], v[212:215], v[86:89]
	v_mfma_f32_16x16x32_bf16 v[82:85], v[172:175], v[212:215], v[82:85]
	v_mfma_f32_16x16x32_bf16 v[70:73], v[164:167], v[220:223], v[70:73]
	v_mfma_f32_16x16x32_bf16 v[66:69], v[172:175], v[220:223], v[66:69]
	s_barrier
; #define PG8_STAGE(bufoff, gbase, voff) do { _Pragma("unroll") for (int _i = 0; _i < 2; ++_i) \
;         __builtin_amdgcn_global_load_lds((const unsigned*)((const char*)(gbase) + (voff)[_i]), (PG8_LAS unsigned*)(lds + (bufoff) + ldsw + _i * 8192), 16, 0, 0); } while (0)
; #define PG8_LDA(dst, b, h) do { _Pragma("unroll") for (int m = 0; m < 4; ++m) _Pragma("unroll") for (int k = 0; k < 2; ++k) dst[m][k] = *(const PG8_LAS bf16x8*)(lds + PG8_SA(b, h) + aoff + m * 2048 + k * 1024); } while (0)
; #define PG8_MMA(ai, bj, At, Bt) do { __builtin_amdgcn_s_setprio(1); _Pragma("unroll") for (int m = 0; m < 4; ++m) _Pragma("unroll") for (int n = 0; n < 2; ++n) _Pragma("unroll") for (int k = 0; k < 2; ++k) \
;         acc[ai][bj][m][n] = __builtin_amdgcn_mfma_f32_16x16x32_bf16(Bt[n][k], At[m][k], acc[ai][bj][m][n], 0, 0, 0); __builtin_amdgcn_s_setprio(0); } while (0)
; #define PG8_WAIT_V(n) asm volatile("s_waitcnt vmcnt(" #n ")" ::: "memory")
; #define PG8_WAIT_L(n) asm volatile("s_waitcnt lgkmcnt(" #n ")" ::: "memory")
; #define PG8_BAR __builtin_amdgcn_s_barrier()
; #define PG8_SCHED __builtin_amdgcn_sched_barrier(0)
; template <class Epi, class Sched, bool ALIGN_EPI = false, bool SP2 = false>
; __device__ __forceinline__ void gemm_phase(PG8_LAS unsigned char* lds, const Gemm g, const Sched& S, const Epi& E, int wid_in) {
;     ...
;             PG8_LDA(At, 1, 1); PG8_STAGE(PG8_SB(1, 0), b3, voffB); PG8_STAGE(PG8_SB(1, 1), b3 + hstep, voffB); PG8_STAGE(PG8_SA(1, 0), a3, voffA);
;             PG8_WAIT_V(8); PG8_WAIT_L(0); PG8_BAR; PG8_MMA(1, 0, At, B0); PG8_MMA(1, 1, At, B1); PG8_BAR; PG8_SCHED;
;     ...
;         if constexpr (ALIGN_EPI) { if (wr == 0) PG8_BAR; }
	s_add_i32 s28, s40, s59
	v_lshl_add_u64 v[140:141], v[140:141], 0, s[94:95]
	s_mov_b32 m0, s28
	ds_read_b128 v[176:179], v143 offset:49152
	ds_read_b128 v[180:183], v143 offset:50176
	ds_read_b128 v[184:187], v143 offset:51200
	ds_read_b128 v[188:191], v143 offset:52224
	ds_read_b128 v[208:211], v143 offset:53248
	ds_read_b128 v[212:215], v143 offset:54272
	ds_read_b128 v[216:219], v143 offset:55296
	ds_read_b128 v[220:223], v143 offset:56320
	global_load_lds_dwordx4 v[140:141], off
	s_add_i32 m0, s28, 0x2000
	s_add_u32 s26, s26, 0x80080
	v_lshl_add_u64 v[140:141], v[192:193], 0, s[94:95]
	s_addc_u32 s27, s27, 0
	s_add_i32 s28, s41, s59
	global_load_lds_dwordx4 v[140:141], off
	v_lshl_add_u64 v[140:141], s[26:27], 0, v[0:1]
	s_mov_b32 m0, s28
	s_nop 0
	global_load_lds_dwordx4 v[140:141], off
	v_lshl_add_u64 v[140:141], s[26:27], 0, v[130:131]
	s_add_i32 m0, s28, 0x2000
	s_nop 0
	global_load_lds_dwordx4 v[140:141], off
	v_lshl_add_u64 v[140:141], v[224:225], 0, s[94:95]
	s_mov_b32 m0, s48
	s_nop 0
	global_load_lds_dwordx4 v[140:141], off
	v_lshl_add_u64 v[140:141], v[226:227], 0, s[94:95]
	s_mov_b32 m0, s52
	s_nop 0
	global_load_lds_dwordx4 v[140:141], off
	s_waitcnt vmcnt(8)
	s_waitcnt lgkmcnt(0)
	s_barrier
	v_mfma_f32_16x16x32_bf16 v[62:65], v[144:147], v[176:179], v[62:65]
	v_mfma_f32_16x16x32_bf16 v[58:61], v[152:155], v[176:179], v[58:61]
	v_mfma_f32_16x16x32_bf16 v[46:49], v[144:147], v[184:187], v[46:49]
	v_mfma_f32_16x16x32_bf16 v[42:45], v[152:155], v[184:187], v[42:45]
	v_mfma_f32_16x16x32_bf16 v[30:33], v[144:147], v[208:211], v[30:33]
	v_mfma_f32_16x16x32_bf16 v[26:29], v[152:155], v[208:211], v[26:29]
	v_mfma_f32_16x16x32_bf16 v[14:17], v[144:147], v[216:219], v[14:17]
	v_mfma_f32_16x16x32_bf16 v[10:13], v[152:155], v[216:219], v[10:13]
	v_mfma_f32_16x16x32_bf16 v[62:65], v[148:151], v[180:183], v[62:65]
	v_mfma_f32_16x16x32_bf16 v[58:61], v[156:159], v[180:183], v[58:61]
	v_mfma_f32_16x16x32_bf16 v[46:49], v[148:151], v[188:191], v[46:49]
	v_mfma_f32_16x16x32_bf16 v[42:45], v[156:159], v[188:191], v[42:45]
	v_mfma_f32_16x16x32_bf16 v[30:33], v[148:151], v[212:215], v[30:33]
	v_mfma_f32_16x16x32_bf16 v[26:29], v[156:159], v[212:215], v[26:29]
	v_mfma_f32_16x16x32_bf16 v[14:17], v[148:151], v[220:223], v[14:17]
	v_mfma_f32_16x16x32_bf16 v[10:13], v[156:159], v[220:223], v[10:13]
	v_mfma_f32_16x16x32_bf16 v[54:57], v[160:163], v[176:179], v[54:57]
	v_mfma_f32_16x16x32_bf16 v[50:53], v[168:171], v[176:179], v[50:53]
	v_mfma_f32_16x16x32_bf16 v[38:41], v[160:163], v[184:187], v[38:41]
	v_mfma_f32_16x16x32_bf16 v[34:37], v[168:171], v[184:187], v[34:37]
	v_mfma_f32_16x16x32_bf16 v[22:25], v[160:163], v[208:211], v[22:25]
	v_mfma_f32_16x16x32_bf16 v[18:21], v[168:171], v[208:211], v[18:21]
	v_mfma_f32_16x16x32_bf16 v[6:9], v[160:163], v[216:219], v[6:9]
	v_mfma_f32_16x16x32_bf16 v[2:5], v[168:171], v[216:219], v[2:5]
	v_mfma_f32_16x16x32_bf16 v[54:57], v[164:167], v[180:183], v[54:57]
	v_mfma_f32_16x16x32_bf16 v[50:53], v[172:175], v[180:183], v[50:53]
	v_mfma_f32_16x16x32_bf16 v[38:41], v[164:167], v[188:191], v[38:41]
	v_mfma_f32_16x16x32_bf16 v[34:37], v[172:175], v[188:191], v[34:37]
	v_mfma_f32_16x16x32_bf16 v[22:25], v[164:167], v[212:215], v[22:25]
	v_mfma_f32_16x16x32_bf16 v[18:21], v[172:175], v[212:215], v[18:21]
	v_mfma_f32_16x16x32_bf16 v[6:9], v[164:167], v[220:223], v[6:9]
	v_mfma_f32_16x16x32_bf16 v[2:5], v[172:175], v[220:223], v[2:5]
	s_barrier
	s_add_i32 s73, s73, 2
	s_add_u32 s72, s72, 0x100
	s_addc_u32 s63, s63, 0
	s_add_u32 s24, s24, 0x100
	s_addc_u32 s25, s25, 0
	s_cmp_gt_u32 s73, 29
	s_cbranch_scc0 .LBB0_1153
	s_setprio 0
	s_and_b64 vcc, exec, s[14:15]
	s_cbranch_vccz .LBB0_1156
	s_barrier

; #define PG8_STAGE(bufoff, gbase, voff) do { _Pragma("unroll") for (int _i = 0; _i < 2; ++_i) \
;         __builtin_amdgcn_global_load_lds((const unsigned*)((const char*)(gbase) + (voff)[_i]), (PG8_LAS unsigned*)(lds + (bufoff) + ldsw + _i * 8192), 16, 0, 0); } while (0)
; #define PG8_LDA(dst, b, h) do { _Pragma("unroll") for (int m = 0; m < 4; ++m) _Pragma("unroll") for (int k = 0; k < 2; ++k) dst[m][k] = *(const PG8_LAS bf16x8*)(lds + PG8_SA(b, h) + aoff + m * 2048 + k * 1024); } while (0)
; #define PG8_LDB(dst, b, h) do { _Pragma("unroll") for (int n = 0; n < 2; ++n) _Pragma("unroll") for (int k = 0; k < 2; ++k) dst[n][k] = *(const PG8_LAS bf16x8*)(lds + PG8_SB(b, h) + boff + n * 2048 + k * 1024); } while (0)
; #define PG8_MMA(ai, bj, At, Bt) do { __builtin_amdgcn_s_setprio(1); _Pragma("unroll") for (int m = 0; m < 4; ++m) _Pragma("unroll") for (int n = 0; n < 2; ++n) _Pragma("unroll") for (int k = 0; k < 2; ++k) \
;         acc[ai][bj][m][n] = __builtin_amdgcn_mfma_f32_16x16x32_bf16(Bt[n][k], At[m][k], acc[ai][bj][m][n], 0, 0, 0); __builtin_amdgcn_s_setprio(0); } while (0)
; #define PG8_WAIT_V(n) asm volatile("s_waitcnt vmcnt(" #n ")" ::: "memory")
; #define PG8_BAR __builtin_amdgcn_s_barrier()
; template <class Epi, class Sched, bool ALIGN_EPI = false, bool SP2 = false>
; __device__ __forceinline__ void gemm_phase(PG8_LAS unsigned char* lds, const Gemm g, const Sched& S, const Epi& E, int wid_in) {
;     ...
;         for (int t = 0; t < nt; t += 2) {
;             const bool last = (t == nt - 2);
;             const char* a1 = cA + (size_t)(t + 1) * kstep;
;             const char* a2 = last ? nA : cA + (size_t)(t + 2) * kstep; const char* b2 = last ? nB : cB + (size_t)(t + 2) * kstep;
;             const char* a3 = a2 + kstep; const char* b3 = b2 + kstep;
;             if (last && has_next) S.a_ready(nxt);
;             if constexpr (SP2) {
;             PG8_LDB(B0, 0, 0); PG8_LDB(B1, 0, 1); PG8_SCHED; PG8_LDA(At, 0, 0); PG8_STAGE(PG8_SA(1, 1), a1 + hstep, voffA);
;             PG8_WAIT_V(8); PG8_WAIT_L(0); PG8_BAR; PG8_MMA(0, 0, At, B0); PG8_MMA(0, 1, At, B1); PG8_BAR; PG8_SCHED;
;             PG8_LDA(At, 0, 1); PG8_STAGE(PG8_SB(0, 0), b2, voffB); PG8_STAGE(PG8_SB(0, 1), b2 + hstep, voffB); PG8_STAGE(PG8_SA(0, 0), a2, voffA);
;             PG8_WAIT_V(8); PG8_WAIT_L(0); PG8_BAR; PG8_MMA(1, 0, At, B0); PG8_MMA(1, 1, At, B1); PG8_BAR; PG8_SCHED;
.Lprio_skip_5:
.LBB0_1233:
	s_add_i32 s56, s27, 2
	s_add_u32 s34, s30, 0xffe00080
	s_addc_u32 s35, s31, -1
	s_add_i32 s40, 0, 0x10000
	s_cmp_eq_u32 s17, s27
	s_cselect_b32 s37, s23, s35
	s_cselect_b32 s36, s22, s34
	s_cselect_b32 s35, s25, s21
	s_cselect_b32 s34, s24, s19
	s_add_i32 s27, 0, 0x14000
	v_add_u32_e32 v142, s40, v176
	v_add_u32_e32 v168, s27, v176
	ds_read_b128 v[130:133], v142
	ds_read_b128 v[134:137], v142 offset:1024
	ds_read_b128 v[138:141], v142 offset:2048
	ds_read_b128 v[142:145], v142 offset:3072
	ds_read_b128 v[146:149], v168
	ds_read_b128 v[160:163], v168 offset:1024
	ds_read_b128 v[164:167], v168 offset:2048
	ds_read_b128 v[168:171], v168 offset:3072
	v_lshl_add_u64 v[220:221], s[30:31], 0, v[158:159]
	s_add_i32 m0, s29, 0xc000
	ds_read_b128 v[172:175], v177
	ds_read_b128 v[178:181], v177 offset:1024
	ds_read_b128 v[182:185], v177 offset:2048
	ds_read_b128 v[186:189], v177 offset:3072
	ds_read_b128 v[190:193], v177 offset:4096
	ds_read_b128 v[208:211], v177 offset:5120
	ds_read_b128 v[212:215], v177 offset:6144
	ds_read_b128 v[216:219], v177 offset:7168
	global_load_lds_dwordx4 v[220:221], off
	v_lshl_add_u64 v[220:221], s[30:31], 0, v[156:157]
	s_add_i32 m0, s29, 0xe000
	s_nop 0
	global_load_lds_dwordx4 v[220:221], off
	s_waitcnt vmcnt(8)
	s_waitcnt lgkmcnt(0)
	s_barrier
	v_mfma_f32_16x16x32_bf16 v[126:129], v[130:133], v[172:175], v[126:129]
	v_mfma_f32_16x16x32_bf16 v[122:125], v[138:141], v[172:175], v[122:125]
	v_mfma_f32_16x16x32_bf16 v[118:121], v[130:133], v[182:185], v[118:121]
	v_mfma_f32_16x16x32_bf16 v[114:117], v[138:141], v[182:185], v[114:117]
	v_mfma_f32_16x16x32_bf16 v[102:105], v[130:133], v[190:193], v[102:105]
	v_mfma_f32_16x16x32_bf16 v[98:101], v[138:141], v[190:193], v[98:101]
	v_mfma_f32_16x16x32_bf16 v[86:89], v[130:133], v[212:215], v[86:89]
	v_mfma_f32_16x16x32_bf16 v[82:85], v[138:141], v[212:215], v[82:85]
	v_mfma_f32_16x16x32_bf16 v[126:129], v[134:137], v[178:181], v[126:129]
	v_mfma_f32_16x16x32_bf16 v[122:125], v[142:145], v[178:181], v[122:125]
	v_mfma_f32_16x16x32_bf16 v[118:121], v[134:137], v[186:189], v[118:121]
	v_mfma_f32_16x16x32_bf16 v[114:117], v[142:145], v[186:189], v[114:117]
	v_mfma_f32_16x16x32_bf16 v[102:105], v[134:137], v[208:211], v[102:105]
	v_mfma_f32_16x16x32_bf16 v[98:101], v[142:145], v[208:211], v[98:101]
	v_mfma_f32_16x16x32_bf16 v[86:89], v[134:137], v[216:219], v[86:89]
	v_mfma_f32_16x16x32_bf16 v[82:85], v[142:145], v[216:219], v[82:85]
	v_mfma_f32_16x16x32_bf16 v[110:113], v[146:149], v[172:175], v[110:113]
	v_mfma_f32_16x16x32_bf16 v[106:109], v[164:167], v[172:175], v[106:109]
	v_mfma_f32_16x16x32_bf16 v[94:97], v[146:149], v[182:185], v[94:97]
	v_mfma_f32_16x16x32_bf16 v[90:93], v[164:167], v[182:185], v[90:93]
	v_mfma_f32_16x16x32_bf16 v[78:81], v[146:149], v[190:193], v[78:81]
	v_mfma_f32_16x16x32_bf16 v[74:77], v[164:167], v[190:193], v[74:77]
	v_mfma_f32_16x16x32_bf16 v[70:73], v[146:149], v[212:215], v[70:73]
	v_mfma_f32_16x16x32_bf16 v[66:69], v[164:167], v[212:215], v[66:69]
	v_mfma_f32_16x16x32_bf16 v[110:113], v[160:163], v[178:181], v[110:113]
	v_mfma_f32_16x16x32_bf16 v[106:109], v[168:171], v[178:181], v[106:109]
	v_mfma_f32_16x16x32_bf16 v[94:97], v[160:163], v[186:189], v[94:97]
	v_mfma_f32_16x16x32_bf16 v[90:93], v[168:171], v[186:189], v[90:93]
	v_mfma_f32_16x16x32_bf16 v[78:81], v[160:163], v[208:211], v[78:81]
	v_mfma_f32_16x16x32_bf16 v[74:77], v[168:171], v[208:211], v[74:77]
	v_mfma_f32_16x16x32_bf16 v[70:73], v[160:163], v[216:219], v[70:73]
	v_mfma_f32_16x16x32_bf16 v[66:69], v[168:171], v[216:219], v[66:69]
	s_barrier
	s_add_i32 s40, s40, s59
	v_lshl_add_u64 v[220:221], s[34:35], 0, v[0:1]
	s_mov_b32 m0, s40
	ds_read_b128 v[172:175], v177 offset:16384
	ds_read_b128 v[178:181], v177 offset:17408
	ds_read_b128 v[182:185], v177 offset:18432
	ds_read_b128 v[186:189], v177 offset:19456
	ds_read_b128 v[190:193], v177 offset:20480
	ds_read_b128 v[208:211], v177 offset:21504
	ds_read_b128 v[212:215], v177 offset:22528
	ds_read_b128 v[216:219], v177 offset:23552
	global_load_lds_dwordx4 v[220:221], off
	s_add_i32 m0, s40, 0x2000
	s_add_u32 s40, s34, 0x200000
	v_lshl_add_u64 v[222:223], s[34:35], 0, v[154:155]
	s_addc_u32 s41, s35, 0
	s_add_i32 s27, s27, s59
	global_load_lds_dwordx4 v[222:223], off
	v_lshl_add_u64 v[224:225], s[40:41], 0, v[0:1]
	s_mov_b32 m0, s27
	v_lshl_add_u64 v[226:227], s[36:37], 0, v[152:153]
	global_load_lds_dwordx4 v[224:225], off
	v_lshl_add_u64 v[224:225], s[40:41], 0, v[154:155]
	s_add_i32 m0, s27, 0x2000
	s_nop 0
	global_load_lds_dwordx4 v[224:225], off
	v_lshl_add_u64 v[224:225], s[36:37], 0, v[150:151]
	s_mov_b32 m0, s29
	s_nop 0
	global_load_lds_dwordx4 v[224:225], off
	s_mov_b32 m0, s52
	s_nop 0
	global_load_lds_dwordx4 v[226:227], off
	s_waitcnt vmcnt(8)
	s_waitcnt lgkmcnt(0)
	s_barrier
; #define PG8_STAGE(bufoff, gbase, voff) do { _Pragma("unroll") for (int _i = 0; _i < 2; ++_i) \
;         __builtin_amdgcn_global_load_lds((const unsigned*)((const char*)(gbase) + (voff)[_i]), (PG8_LAS unsigned*)(lds + (bufoff) + ldsw + _i * 8192), 16, 0, 0); } while (0)
; #define PG8_LDA(dst, b, h) do { _Pragma("unroll") for (int m = 0; m < 4; ++m) _Pragma("unroll") for (int k = 0; k < 2; ++k) dst[m][k] = *(const PG8_LAS bf16x8*)(lds + PG8_SA(b, h) + aoff + m * 2048 + k * 1024); } while (0)
; #define PG8_LDB(dst, b, h) do { _Pragma("unroll") for (int n = 0; n < 2; ++n) _Pragma("unroll") for (int k = 0; k < 2; ++k) dst[n][k] = *(const PG8_LAS bf16x8*)(lds + PG8_SB(b, h) + boff + n * 2048 + k * 1024); } while (0)
; #define PG8_MMA(ai, bj, At, Bt) do { __builtin_amdgcn_s_setprio(1); _Pragma("unroll") for (int m = 0; m < 4; ++m) _Pragma("unroll") for (int n = 0; n < 2; ++n) _Pragma("unroll") for (int k = 0; k < 2; ++k) \
;         acc[ai][bj][m][n] = __builtin_amdgcn_mfma_f32_16x16x32_bf16(Bt[n][k], At[m][k], acc[ai][bj][m][n], 0, 0, 0); __builtin_amdgcn_s_setprio(0); } while (0)
; #define PG8_WAIT_V(n) asm volatile("s_waitcnt vmcnt(" #n ")" ::: "memory")
; #define PG8_WAIT_L(n) asm volatile("s_waitcnt lgkmcnt(" #n ")" ::: "memory")
; #define PG8_BAR __builtin_amdgcn_s_barrier()
; #define PG8_SCHED __builtin_amdgcn_sched_barrier(0)
; template <class Epi, class Sched, bool ALIGN_EPI = false, bool SP2 = false>
; __device__ __forceinline__ void gemm_phase(PG8_LAS unsigned char* lds, const Gemm g, const Sched& S, const Epi& E, int wid_in) {
;     ...
;             PG8_WAIT_V(8); PG8_WAIT_L(0); PG8_BAR; PG8_MMA(1, 0, At, B0); PG8_MMA(1, 1, At, B1); PG8_BAR; PG8_SCHED;
;             PG8_LDB(B0, 1, 0); PG8_LDB(B1, 1, 1); PG8_SCHED; PG8_LDA(At, 1, 0); PG8_STAGE(PG8_SA(0, 1), a2 + hstep, voffA);
;             PG8_WAIT_V(8); PG8_WAIT_L(0); PG8_BAR; PG8_MMA(0, 0, At, B0); PG8_MMA(0, 1, At, B1); PG8_BAR; PG8_SCHED;
	v_mfma_f32_16x16x32_bf16 v[62:65], v[130:133], v[172:175], v[62:65]
	v_mfma_f32_16x16x32_bf16 v[58:61], v[138:141], v[172:175], v[58:61]
	v_mfma_f32_16x16x32_bf16 v[54:57], v[130:133], v[182:185], v[54:57]
	v_mfma_f32_16x16x32_bf16 v[50:53], v[138:141], v[182:185], v[50:53]
	v_mfma_f32_16x16x32_bf16 v[38:41], v[130:133], v[190:193], v[38:41]
	v_mfma_f32_16x16x32_bf16 v[34:37], v[138:141], v[190:193], v[34:37]
	v_mfma_f32_16x16x32_bf16 v[22:25], v[130:133], v[212:215], v[22:25]
	v_mfma_f32_16x16x32_bf16 v[18:21], v[138:141], v[212:215], v[18:21]
	v_mfma_f32_16x16x32_bf16 v[62:65], v[134:137], v[178:181], v[62:65]
	v_mfma_f32_16x16x32_bf16 v[58:61], v[142:145], v[178:181], v[58:61]
	v_mfma_f32_16x16x32_bf16 v[54:57], v[134:137], v[186:189], v[54:57]
	v_mfma_f32_16x16x32_bf16 v[50:53], v[142:145], v[186:189], v[50:53]
	v_mfma_f32_16x16x32_bf16 v[38:41], v[134:137], v[208:211], v[38:41]
	v_mfma_f32_16x16x32_bf16 v[34:37], v[142:145], v[208:211], v[34:37]
	v_mfma_f32_16x16x32_bf16 v[22:25], v[134:137], v[216:219], v[22:25]
	v_mfma_f32_16x16x32_bf16 v[18:21], v[142:145], v[216:219], v[18:21]
	v_mfma_f32_16x16x32_bf16 v[46:49], v[146:149], v[172:175], v[46:49]
	v_mfma_f32_16x16x32_bf16 v[42:45], v[164:167], v[172:175], v[42:45]
	v_mfma_f32_16x16x32_bf16 v[30:33], v[146:149], v[182:185], v[30:33]
	v_mfma_f32_16x16x32_bf16 v[26:29], v[164:167], v[182:185], v[26:29]
	v_mfma_f32_16x16x32_bf16 v[14:17], v[146:149], v[190:193], v[14:17]
	v_mfma_f32_16x16x32_bf16 v[10:13], v[164:167], v[190:193], v[10:13]
	v_mfma_f32_16x16x32_bf16 v[6:9], v[146:149], v[212:215], v[6:9]
	v_mfma_f32_16x16x32_bf16 v[2:5], v[164:167], v[212:215], v[2:5]
	v_mfma_f32_16x16x32_bf16 v[46:49], v[160:163], v[178:181], v[46:49]
	v_mfma_f32_16x16x32_bf16 v[42:45], v[168:171], v[178:181], v[42:45]
	v_mfma_f32_16x16x32_bf16 v[30:33], v[160:163], v[186:189], v[30:33]
	v_mfma_f32_16x16x32_bf16 v[26:29], v[168:171], v[186:189], v[26:29]
	v_mfma_f32_16x16x32_bf16 v[14:17], v[160:163], v[208:211], v[14:17]
	v_mfma_f32_16x16x32_bf16 v[10:13], v[168:171], v[208:211], v[10:13]
	v_mfma_f32_16x16x32_bf16 v[6:9], v[160:163], v[216:219], v[6:9]
	v_mfma_f32_16x16x32_bf16 v[2:5], v[168:171], v[216:219], v[2:5]
	s_barrier
	s_add_i32 s27, 0, 0x18000
	s_add_i32 s40, 0, 0x1c000
	v_add_u32_e32 v142, s27, v176
	v_add_u32_e32 v168, s40, v176
	ds_read_b128 v[130:133], v142
	ds_read_b128 v[134:137], v142 offset:1024
	ds_read_b128 v[138:141], v142 offset:2048
	ds_read_b128 v[142:145], v142 offset:3072
	ds_read_b128 v[146:149], v168
	ds_read_b128 v[160:163], v168 offset:1024
	ds_read_b128 v[164:167], v168 offset:2048
	ds_read_b128 v[168:171], v168 offset:3072
	s_add_u32 s36, s36, 0x200000
	s_addc_u32 s37, s37, 0
	s_mov_b32 m0, s53
	v_lshl_add_u64 v[228:229], s[36:37], 0, v[150:151]
	ds_read_b128 v[172:175], v177 offset:32768
	ds_read_b128 v[178:181], v177 offset:33792
	ds_read_b128 v[182:185], v177 offset:34816
	ds_read_b128 v[186:189], v177 offset:35840
	ds_read_b128 v[190:193], v177 offset:36864
	ds_read_b128 v[208:211], v177 offset:37888
	ds_read_b128 v[212:215], v177 offset:38912
	ds_read_b128 v[216:219], v177 offset:39936
	global_load_lds_dwordx4 v[228:229], off
	v_lshl_add_u64 v[228:229], s[36:37], 0, v[152:153]
	s_mov_b32 m0, s61
	s_nop 0
	global_load_lds_dwordx4 v[228:229], off
	s_waitcnt vmcnt(8)
	s_waitcnt lgkmcnt(0)
	s_barrier
	v_mfma_f32_16x16x32_bf16 v[126:129], v[130:133], v[172:175], v[126:129]
	v_mfma_f32_16x16x32_bf16 v[122:125], v[138:141], v[172:175], v[122:125]
	v_mfma_f32_16x16x32_bf16 v[118:121], v[130:133], v[182:185], v[118:121]
	v_mfma_f32_16x16x32_bf16 v[114:117], v[138:141], v[182:185], v[114:117]
	v_mfma_f32_16x16x32_bf16 v[102:105], v[130:133], v[190:193], v[102:105]
	v_mfma_f32_16x16x32_bf16 v[98:101], v[138:141], v[190:193], v[98:101]
	v_mfma_f32_16x16x32_bf16 v[86:89], v[130:133], v[212:215], v[86:89]
	v_mfma_f32_16x16x32_bf16 v[82:85], v[138:141], v[212:215], v[82:85]
	v_mfma_f32_16x16x32_bf16 v[126:129], v[134:137], v[178:181], v[126:129]
	v_mfma_f32_16x16x32_bf16 v[122:125], v[142:145], v[178:181], v[122:125]
	v_mfma_f32_16x16x32_bf16 v[118:121], v[134:137], v[186:189], v[118:121]
	v_mfma_f32_16x16x32_bf16 v[114:117], v[142:145], v[186:189], v[114:117]
	v_mfma_f32_16x16x32_bf16 v[102:105], v[134:137], v[208:211], v[102:105]
	v_mfma_f32_16x16x32_bf16 v[98:101], v[142:145], v[208:211], v[98:101]
	v_mfma_f32_16x16x32_bf16 v[86:89], v[134:137], v[216:219], v[86:89]
	v_mfma_f32_16x16x32_bf16 v[82:85], v[142:145], v[216:219], v[82:85]
	v_mfma_f32_16x16x32_bf16 v[110:113], v[146:149], v[172:175], v[110:113]
	v_mfma_f32_16x16x32_bf16 v[106:109], v[164:167], v[172:175], v[106:109]
	v_mfma_f32_16x16x32_bf16 v[94:97], v[146:149], v[182:185], v[94:97]
	v_mfma_f32_16x16x32_bf16 v[90:93], v[164:167], v[182:185], v[90:93]
	v_mfma_f32_16x16x32_bf16 v[78:81], v[146:149], v[190:193], v[78:81]
	v_mfma_f32_16x16x32_bf16 v[74:77], v[164:167], v[190:193], v[74:77]
	v_mfma_f32_16x16x32_bf16 v[70:73], v[146:149], v[212:215], v[70:73]
	v_mfma_f32_16x16x32_bf16 v[66:69], v[164:167], v[212:215], v[66:69]
	v_mfma_f32_16x16x32_bf16 v[110:113], v[160:163], v[178:181], v[110:113]
	v_mfma_f32_16x16x32_bf16 v[106:109], v[168:171], v[178:181], v[106:109]
	v_mfma_f32_16x16x32_bf16 v[94:97], v[160:163], v[186:189], v[94:97]
	v_mfma_f32_16x16x32_bf16 v[90:93], v[168:171], v[186:189], v[90:93]
	v_mfma_f32_16x16x32_bf16 v[78:81], v[160:163], v[208:211], v[78:81]
	v_mfma_f32_16x16x32_bf16 v[74:77], v[168:171], v[208:211], v[74:77]
	v_mfma_f32_16x16x32_bf16 v[70:73], v[160:163], v[216:219], v[70:73]
	v_mfma_f32_16x16x32_bf16 v[66:69], v[168:171], v[216:219], v[66:69]
	s_barrier
; #define PG8_STAGE(bufoff, gbase, voff) do { _Pragma("unroll") for (int _i = 0; _i < 2; ++_i) \
;         __builtin_amdgcn_global_load_lds((const unsigned*)((const char*)(gbase) + (voff)[_i]), (PG8_LAS unsigned*)(lds + (bufoff) + ldsw + _i * 8192), 16, 0, 0); } while (0)
; #define PG8_LDA(dst, b, h) do { _Pragma("unroll") for (int m = 0; m < 4; ++m) _Pragma("unroll") for (int k = 0; k < 2; ++k) dst[m][k] = *(const PG8_LAS bf16x8*)(lds + PG8_SA(b, h) + aoff + m * 2048 + k * 1024); } while (0)
; #define PG8_MMA(ai, bj, At, Bt) do { __builtin_amdgcn_s_setprio(1); _Pragma("unroll") for (int m = 0; m < 4; ++m) _Pragma("unroll") for (int n = 0; n < 2; ++n) _Pragma("unroll") for (int k = 0; k < 2; ++k) \
;         acc[ai][bj][m][n] = __builtin_amdgcn_mfma_f32_16x16x32_bf16(Bt[n][k], At[m][k], acc[ai][bj][m][n], 0, 0, 0); __builtin_amdgcn_s_setprio(0); } while (0)
; #define PG8_WAIT_V(n) asm volatile("s_waitcnt vmcnt(" #n ")" ::: "memory")
; #define PG8_WAIT_L(n) asm volatile("s_waitcnt lgkmcnt(" #n ")" ::: "memory")
; #define PG8_BAR __builtin_amdgcn_s_barrier()
; #define PG8_SCHED __builtin_amdgcn_sched_barrier(0)
; template <class Epi, class Sched, bool ALIGN_EPI = false, bool SP2 = false>
; __device__ __forceinline__ void gemm_phase(PG8_LAS unsigned char* lds, const Gemm g, const Sched& S, const Epi& E, int wid_in) {
;     ...
;             PG8_LDA(At, 1, 1); PG8_STAGE(PG8_SB(1, 0), b3, voffB); PG8_STAGE(PG8_SB(1, 1), b3 + hstep, voffB); PG8_STAGE(PG8_SA(1, 0), a3, voffA);
;             PG8_WAIT_V(8); PG8_WAIT_L(0); PG8_BAR; PG8_MMA(1, 0, At, B0); PG8_MMA(1, 1, At, B1); PG8_BAR; PG8_SCHED;
;     ...
;         if constexpr (ALIGN_EPI) { if (wr == 0) PG8_BAR; }
	s_add_i32 s27, s27, s59
	v_lshl_add_u64 v[220:221], v[220:221], 0, s[94:95]
	s_mov_b32 m0, s27
	ds_read_b128 v[172:175], v177 offset:49152
	ds_read_b128 v[178:181], v177 offset:50176
	ds_read_b128 v[182:185], v177 offset:51200
	ds_read_b128 v[186:189], v177 offset:52224
	ds_read_b128 v[190:193], v177 offset:53248
	ds_read_b128 v[208:211], v177 offset:54272
	ds_read_b128 v[212:215], v177 offset:55296
	ds_read_b128 v[216:219], v177 offset:56320
	global_load_lds_dwordx4 v[220:221], off
	s_add_i32 m0, s27, 0x2000
	s_add_u32 s34, s34, 0x200080
	v_lshl_add_u64 v[220:221], v[222:223], 0, s[94:95]
	s_addc_u32 s35, s35, 0
	s_add_i32 s27, s40, s59
	global_load_lds_dwordx4 v[220:221], off
	v_lshl_add_u64 v[220:221], s[34:35], 0, v[0:1]
	s_mov_b32 m0, s27
	s_nop 0
	global_load_lds_dwordx4 v[220:221], off
	v_lshl_add_u64 v[220:221], s[34:35], 0, v[154:155]
	s_add_i32 m0, s27, 0x2000
	s_nop 0
	global_load_lds_dwordx4 v[220:221], off
	v_lshl_add_u64 v[220:221], v[224:225], 0, s[94:95]
	s_mov_b32 m0, s73
	s_nop 0
	global_load_lds_dwordx4 v[220:221], off
	v_lshl_add_u64 v[220:221], v[226:227], 0, s[94:95]
	s_mov_b32 m0, s80
	s_nop 0
	global_load_lds_dwordx4 v[220:221], off
	s_waitcnt vmcnt(8)
	s_waitcnt lgkmcnt(0)
	s_barrier
	v_mfma_f32_16x16x32_bf16 v[62:65], v[130:133], v[172:175], v[62:65]
	v_mfma_f32_16x16x32_bf16 v[58:61], v[138:141], v[172:175], v[58:61]
	v_mfma_f32_16x16x32_bf16 v[54:57], v[130:133], v[182:185], v[54:57]
	v_mfma_f32_16x16x32_bf16 v[50:53], v[138:141], v[182:185], v[50:53]
	v_mfma_f32_16x16x32_bf16 v[38:41], v[130:133], v[190:193], v[38:41]
	v_mfma_f32_16x16x32_bf16 v[34:37], v[138:141], v[190:193], v[34:37]
	v_mfma_f32_16x16x32_bf16 v[22:25], v[130:133], v[212:215], v[22:25]
	v_mfma_f32_16x16x32_bf16 v[18:21], v[138:141], v[212:215], v[18:21]
	v_mfma_f32_16x16x32_bf16 v[62:65], v[134:137], v[178:181], v[62:65]
	v_mfma_f32_16x16x32_bf16 v[58:61], v[142:145], v[178:181], v[58:61]
	v_mfma_f32_16x16x32_bf16 v[54:57], v[134:137], v[186:189], v[54:57]
	v_mfma_f32_16x16x32_bf16 v[50:53], v[142:145], v[186:189], v[50:53]
	v_mfma_f32_16x16x32_bf16 v[38:41], v[134:137], v[208:211], v[38:41]
	v_mfma_f32_16x16x32_bf16 v[34:37], v[142:145], v[208:211], v[34:37]
	v_mfma_f32_16x16x32_bf16 v[22:25], v[134:137], v[216:219], v[22:25]
	v_mfma_f32_16x16x32_bf16 v[18:21], v[142:145], v[216:219], v[18:21]
	v_mfma_f32_16x16x32_bf16 v[46:49], v[146:149], v[172:175], v[46:49]
	v_mfma_f32_16x16x32_bf16 v[42:45], v[164:167], v[172:175], v[42:45]
	v_mfma_f32_16x16x32_bf16 v[30:33], v[146:149], v[182:185], v[30:33]
	v_mfma_f32_16x16x32_bf16 v[26:29], v[164:167], v[182:185], v[26:29]
	v_mfma_f32_16x16x32_bf16 v[14:17], v[146:149], v[190:193], v[14:17]
	v_mfma_f32_16x16x32_bf16 v[10:13], v[164:167], v[190:193], v[10:13]
	v_mfma_f32_16x16x32_bf16 v[6:9], v[146:149], v[212:215], v[6:9]
	v_mfma_f32_16x16x32_bf16 v[2:5], v[164:167], v[212:215], v[2:5]
	v_mfma_f32_16x16x32_bf16 v[46:49], v[160:163], v[178:181], v[46:49]
	v_mfma_f32_16x16x32_bf16 v[42:45], v[168:171], v[178:181], v[42:45]
	v_mfma_f32_16x16x32_bf16 v[30:33], v[160:163], v[186:189], v[30:33]
	v_mfma_f32_16x16x32_bf16 v[26:29], v[168:171], v[186:189], v[26:29]
	v_mfma_f32_16x16x32_bf16 v[14:17], v[160:163], v[208:211], v[14:17]
	v_mfma_f32_16x16x32_bf16 v[10:13], v[168:171], v[208:211], v[10:13]
	v_mfma_f32_16x16x32_bf16 v[6:9], v[160:163], v[216:219], v[6:9]
	v_mfma_f32_16x16x32_bf16 v[2:5], v[168:171], v[216:219], v[2:5]
	s_barrier
	s_add_u32 s19, s19, 0x100
	s_addc_u32 s21, s21, 0
	s_add_u32 s30, s30, 0x100
	s_addc_u32 s31, s31, 0
	s_cmp_ge_i32 s56, s90
	s_mov_b32 s27, s56
	s_cbranch_scc0 .LBB0_1233
	s_setprio 0
	s_and_b64 vcc, exec, s[14:15]
	s_cbranch_vccz .LBB0_1236
	s_barrier
